# attention fast path with two staging register sets (tile loads two steps ahead, vmcnt(9)), K ring of 5, V ring of 4
# speedup vs baseline: 1.1154x; 1.0003x over previous
; __device__ __forceinline__ int tid_() { int t = threadIdx.x; asm volatile("" : "+v"(t)); return t; }
; __device__ __forceinline__ void attn_item(const Params& p, int b, int h, int qt, float shift, unsigned char* smem) {
;     ...
;   const int t = tid_(), lane = t & 63, wid = t >> 6, l16 = lane & 15, quad = lane >> 4;
;   const int nkeys = (qt < 2) ? CTX : NPOS;
;   const int ntile = nkeys >> 5;
;   const u16* Qp = p.Qall + ((size_t)(b * 4 + h) * NPOS + qt * 128 + wid * 32) * 192;
;   const u16* kp = p.Kb + (size_t)(b * 4 + h) * NPOS * 192 + t * 8;
;   const u16* vp = p.Vt + (size_t)(b * 4 + h) * 128 * NPOS + (size_t)(t >> 2) * NPOS + (t & 3) * 8;
;   const u16* qlane = Qp + (size_t)l16 * 192 + quad * 8;
;   bf16x8 bq[2][6];
; #pragma unroll
;   for (int qi = 0; qi < 2; ++qi)
; #pragma unroll
;     for (int ks = 0; ks < 6; ++ks) bq[qi][ks] = *(const bf16x8*)(qlane + qi * 16 * 192 + ks * 32);
;   f32x4 o[8][2];
; #pragma unroll
;   for (int vt = 0; vt < 8; ++vt)
; #pragma unroll
;     for (int qi = 0; qi < 2; ++qi) o[vt][qi] = (f32x4){0.f, 0.f, 0.f, 0.f};
;   float lrun0 = 0.f, lrun1 = 0.f;
;   u32x4 rk[3], rv[2];
;     ...
;   __syncthreads();
;   ATT_LOAD(0);
;   ATT_STORE(0);
;   ATT_LOAD(1);
;   __syncthreads();
;   ATT_S(sA, 0);
;   ATT_STORE(1);
;   __syncthreads();
.Lfa_item:
	s_load_dwordx4 s[52:55], s[4:5], 0x158
	s_load_dwordx2 s[56:57], s[4:5], 0x168
	s_load_dwordx2 s[88:89], s[4:5], 0x128
	v_lshrrev_b32_e32 v0, 6, v187
	v_and_b32_e32 v118, 63, v187
	v_and_b32_e32 v119, 31, v118
	v_lshrrev_b32_e32 v120, 5, v118
	v_readfirstlane_b32 s0, v0
	v_and_b32_e32 v121, 0x13, v119
	v_and_b32_e32 v122, 4, v119
	v_lshl_or_b32 v121, v122, 1, v121
	v_and_b32_e32 v122, 8, v119
	v_lshrrev_b32_e32 v122, 1, v122
	v_or_b32_e32 v121, v121, v122
	v_mul_u32_u24_e32 v121, 0x190, v121
	v_lshl_add_u32 v212, v120, 4, v121
	v_mul_u32_u24_e32 v122, 0x50, v119
	v_lshl_add_u32 v122, v120, 4, v122
	v_add_u32_e32 v213, 0x3200, v122
	v_mul_u32_u24_e32 v122, 0x180, v119
	v_lshl_add_u32 v123, v120, 4, v122
	v_lshlrev_b32_e32 v248, 4, v187
	v_lshrrev_b32_e32 v124, 2, v187
	v_and_b32_e32 v125, 3, v187
	v_mul_u32_u24_e32 v126, 0x4200, v124
	v_lshl_add_u32 v235, v125, 4, v126
	v_mul_u32_u24_e32 v126, 0x50, v124
	v_lshl_add_u32 v126, v125, 4, v126
	v_add_u32_e32 v247, 0x3200, v126
	v_mov_b32_e32 v127, v187
	v_mul_u32_u24_e32 v128, 0xaab, v127
	v_lshrrev_b32_e32 v128, 16, v128
	v_add_lshl_u32 v244, v127, v128, 4
	v_add_u32_e32 v127, 0x100, v187
	v_mul_u32_u24_e32 v128, 0xaab, v127
	v_lshrrev_b32_e32 v128, 16, v128
	v_add_lshl_u32 v245, v127, v128, 4
	v_add_u32_e32 v127, 0x200, v187
	v_mul_u32_u24_e32 v128, 0xaab, v127
	v_lshrrev_b32_e32 v128, 16, v128
	v_add_lshl_u32 v246, v127, v128, 4
	s_waitcnt lgkmcnt(0)
	s_nop 3
	s_lshl_b32 s1, s50, 7
	s_addk_i32 s1, 0x100
	s_lshl_b32 s34, s0, 5
	s_add_i32 s1, s1, s34
	s_add_i32 s34, s1, s9
	s_mul_i32 s34, s34, 0x180
	s_add_u32 s54, s54, s34
	s_addc_u32 s55, s55, 0
	s_add_i32 s34, s48, s1
	s_lshl_b32 s34, s34, 11
	s_add_i32 s34, s34, s46
	s_addk_i32 s34, 0x400
	s_add_u32 s88, s88, s34
	s_addc_u32 s89, s89, 0
	s_add_u32 s56, s56, s40
	s_addc_u32 s57, s57, 0
	s_add_u32 s98, s56, 0x2000
	s_addc_u32 s99, s57, 0
	s_add_u32 s52, s52, s42
	s_addc_u32 s53, s53, 0
	s_add_u32 s100, s52, 0x108000
	s_addc_u32 s101, s53, 0
	s_barrier
	global_load_dwordx4 v[188:191], v248, s[56:57]
	global_load_dwordx4 v[192:195], v248, s[98:99] offset:-4096
	global_load_dwordx4 v[196:199], v248, s[98:99]
	global_load_dwordx4 v[200:203], v235, s[52:53]
	global_load_dwordx4 v[204:207], v235, s[100:101]
	global_load_dwordx4 v[6:9], v123, s[54:55] offset:0
	global_load_dwordx4 v[10:13], v123, s[54:55] offset:32
	global_load_dwordx4 v[14:17], v123, s[54:55] offset:64
	global_load_dwordx4 v[18:21], v123, s[54:55] offset:96
	global_load_dwordx4 v[22:25], v123, s[54:55] offset:128
	global_load_dwordx4 v[26:29], v123, s[54:55] offset:160
	global_load_dwordx4 v[30:33], v123, s[54:55] offset:192
	global_load_dwordx4 v[34:37], v123, s[54:55] offset:224
	global_load_dwordx4 v[38:41], v123, s[54:55] offset:256
	global_load_dwordx4 v[42:45], v123, s[54:55] offset:288
	global_load_dwordx4 v[46:49], v123, s[54:55] offset:320
	global_load_dwordx4 v[50:53], v123, s[54:55] offset:352
	s_add_u32 s56, s56, 0x3000
	s_addc_u32 s57, s57, 0
	s_add_u32 s98, s98, 0x3000
	s_addc_u32 s99, s99, 0
	s_add_u32 s52, s52, 64
	s_addc_u32 s53, s53, 0
	s_add_u32 s100, s100, 64
	s_addc_u32 s101, s101, 0
	s_waitcnt vmcnt(16)
	ds_write_b128 v244, v[188:191] offset:0
	s_waitcnt vmcnt(15)
	ds_write_b128 v245, v[192:195] offset:0
	s_waitcnt vmcnt(14)
	ds_write_b128 v246, v[196:199] offset:0
	s_waitcnt vmcnt(13)
	ds_write_b128 v247, v[200:203] offset:0
	s_waitcnt vmcnt(12)
	ds_write_b128 v247, v[204:207] offset:5120
	global_load_dwordx4 v[188:191], v248, s[56:57]
	global_load_dwordx4 v[192:195], v248, s[98:99] offset:-4096
	global_load_dwordx4 v[196:199], v248, s[98:99]
	global_load_dwordx4 v[200:203], v235, s[52:53]
	global_load_dwordx4 v[204:207], v235, s[100:101]
	s_add_u32 s56, s56, 0x3000
	s_addc_u32 s57, s57, 0
	s_add_u32 s98, s98, 0x3000
	s_addc_u32 s99, s99, 0
	s_add_u32 s52, s52, 64
	s_addc_u32 s53, s53, 0
	s_add_u32 s100, s100, 64
	s_addc_u32 s101, s101, 0
	v_mov_b32_e32 v0, 0
	v_mov_b32_e32 v54, 0
	v_mov_b32_e32 v55, 0
	v_mov_b32_e32 v56, 0
	v_mov_b32_e32 v57, 0
	v_mov_b32_e32 v58, 0
	v_mov_b32_e32 v59, 0
	v_mov_b32_e32 v60, 0
	v_mov_b32_e32 v61, 0
	v_mov_b32_e32 v62, 0
	v_mov_b32_e32 v63, 0
	v_mov_b32_e32 v64, 0
	v_mov_b32_e32 v65, 0
	v_mov_b32_e32 v66, 0
	v_mov_b32_e32 v67, 0
	v_mov_b32_e32 v68, 0
	v_mov_b32_e32 v69, 0
	v_mov_b32_e32 v70, 0
	v_mov_b32_e32 v71, 0
	v_mov_b32_e32 v72, 0
	v_mov_b32_e32 v73, 0
	v_mov_b32_e32 v74, 0
	v_mov_b32_e32 v75, 0
	v_mov_b32_e32 v76, 0
	v_mov_b32_e32 v77, 0
	v_mov_b32_e32 v78, 0
	v_mov_b32_e32 v79, 0
	v_mov_b32_e32 v80, 0
	v_mov_b32_e32 v81, 0
	v_mov_b32_e32 v82, 0
	v_mov_b32_e32 v83, 0
	v_mov_b32_e32 v84, 0
	v_mov_b32_e32 v85, 0
	v_mov_b32_e32 v86, 0
	v_mov_b32_e32 v87, 0
	v_mov_b32_e32 v88, 0
	v_mov_b32_e32 v89, 0
	v_mov_b32_e32 v90, 0
	v_mov_b32_e32 v91, 0
	v_mov_b32_e32 v92, 0
	v_mov_b32_e32 v93, 0
	v_mov_b32_e32 v94, 0
	v_mov_b32_e32 v95, 0
	v_mov_b32_e32 v96, 0
	v_mov_b32_e32 v97, 0
	v_mov_b32_e32 v98, 0
	v_mov_b32_e32 v99, 0
	v_mov_b32_e32 v100, 0
	v_mov_b32_e32 v101, 0
	v_mov_b32_e32 v102, 0
	v_mov_b32_e32 v103, 0
	v_mov_b32_e32 v104, 0
	v_mov_b32_e32 v105, 0
	v_mov_b32_e32 v106, 0
	v_mov_b32_e32 v107, 0
	v_mov_b32_e32 v108, 0
	v_mov_b32_e32 v109, 0
	v_mov_b32_e32 v110, 0
	v_mov_b32_e32 v111, 0
	v_mov_b32_e32 v112, 0
	v_mov_b32_e32 v113, 0
	v_mov_b32_e32 v114, 0
	v_mov_b32_e32 v115, 0
	v_mov_b32_e32 v116, 0
	v_mov_b32_e32 v117, 0
	s_waitcnt vmcnt(4)
	ds_write_b128 v244, v[188:191] offset:23040
	s_waitcnt vmcnt(3)
	ds_write_b128 v245, v[192:195] offset:23040
	s_waitcnt vmcnt(2)
	ds_write_b128 v246, v[196:199] offset:23040
	s_waitcnt vmcnt(1)
	ds_write_b128 v247, v[200:203] offset:23040
	s_waitcnt vmcnt(0)
	ds_write_b128 v247, v[204:207] offset:28160
	global_load_dwordx4 v[188:191], v248, s[56:57]
	global_load_dwordx4 v[192:195], v248, s[98:99] offset:-4096
	global_load_dwordx4 v[196:199], v248, s[98:99]
	global_load_dwordx4 v[200:203], v235, s[52:53]
	global_load_dwordx4 v[204:207], v235, s[100:101]
	s_add_u32 s56, s56, 0x3000
	s_addc_u32 s57, s57, 0
	s_add_u32 s98, s98, 0x3000
	s_addc_u32 s99, s99, 0
	s_add_u32 s52, s52, 64
	s_addc_u32 s53, s53, 0
	s_add_u32 s100, s100, 64
	s_addc_u32 s101, s101, 0
	global_load_dwordx4 v[208:211], v248, s[56:57]
	global_load_dwordx4 v[216:219], v248, s[98:99] offset:-4096
	global_load_dwordx4 v[220:223], v248, s[98:99]
	global_load_dwordx4 v[236:239], v235, s[52:53]
	global_load_dwordx4 v[240:243], v235, s[100:101]
	s_add_u32 s56, s56, 0x3000
	s_addc_u32 s57, s57, 0
	s_add_u32 s98, s98, 0x3000
	s_addc_u32 s99, s99, 0
	s_add_u32 s52, s52, 64
	s_addc_u32 s53, s53, 0
	s_add_u32 s100, s100, 64
	s_addc_u32 s101, s101, 0
	s_waitcnt lgkmcnt(0)
	s_barrier
; __device__ __forceinline__ void attn_item(const Params& p, int b, int h, int qt, float shift, unsigned char* smem) {
;     ...
;   __syncthreads();
;   ATT_LOAD(0);
;   ATT_STORE(0);
;   ATT_LOAD(1);
;   __syncthreads();
;   ATT_S(sA, 0);
;   ATT_STORE(1);
;   __syncthreads();
; #pragma unroll 1
;   for (int tt = 1; tt < ntile - 1; tt += 2) {
;     ATT_STEP(sB, sA, tt);
;     ATT_STEP(sA, sB, tt + 1);
;   }
	ds_read_b128 v[150:153], v212 offset:0
	ds_read_b128 v[154:157], v212 offset:32
	ds_read_b128 v[158:161], v212 offset:64
	ds_read_b128 v[162:165], v212 offset:96
	ds_read_b128 v[166:169], v212 offset:128
	s_waitcnt lgkmcnt(4)
	v_mfma_f32_32x32x16_bf16 v[118:133], v[150:153], v[6:9], 0
	ds_read_b128 v[150:153], v212 offset:160
	s_waitcnt lgkmcnt(4)
	v_mfma_f32_32x32x16_bf16 v[118:133], v[154:157], v[10:13], v[118:133]
	ds_read_b128 v[154:157], v212 offset:192
	s_waitcnt lgkmcnt(4)
	v_mfma_f32_32x32x16_bf16 v[118:133], v[158:161], v[14:17], v[118:133]
	ds_read_b128 v[158:161], v212 offset:224
	s_waitcnt lgkmcnt(4)
	v_mfma_f32_32x32x16_bf16 v[118:133], v[162:165], v[18:21], v[118:133]
	ds_read_b128 v[162:165], v212 offset:256
	s_waitcnt lgkmcnt(4)
	v_mfma_f32_32x32x16_bf16 v[118:133], v[166:169], v[22:25], v[118:133]
	ds_read_b128 v[166:169], v212 offset:288
	s_waitcnt lgkmcnt(4)
	v_mfma_f32_32x32x16_bf16 v[118:133], v[150:153], v[26:29], v[118:133]
	ds_read_b128 v[150:153], v212 offset:320
	s_waitcnt lgkmcnt(4)
	v_mfma_f32_32x32x16_bf16 v[118:133], v[154:157], v[30:33], v[118:133]
	ds_read_b128 v[154:157], v212 offset:352
	s_waitcnt lgkmcnt(4)
	v_mfma_f32_32x32x16_bf16 v[118:133], v[158:161], v[34:37], v[118:133]
	s_waitcnt lgkmcnt(3)
	v_mfma_f32_32x32x16_bf16 v[118:133], v[162:165], v[38:41], v[118:133]
	s_waitcnt lgkmcnt(2)
	v_mfma_f32_32x32x16_bf16 v[118:133], v[166:169], v[42:45], v[118:133]
	s_waitcnt lgkmcnt(1)
	v_mfma_f32_32x32x16_bf16 v[118:133], v[150:153], v[46:49], v[118:133]
	s_waitcnt lgkmcnt(0)
	v_mfma_f32_32x32x16_bf16 v[118:133], v[154:157], v[50:53], v[118:133]
	s_mov_b32 s47, 43
.Lfa_loop:
	ds_read_b128 v[150:153], v212 offset:23040
	ds_read_b128 v[154:157], v212 offset:23072
	ds_read_b128 v[158:161], v212 offset:23104
	ds_read_b128 v[162:165], v212 offset:23136
	ds_read_b128 v[166:169], v212 offset:23168
	s_waitcnt lgkmcnt(4)
	v_mfma_f32_32x32x16_bf16 v[134:149], v[150:153], v[6:9], 0
	ds_read_b128 v[150:153], v212 offset:23200
	ds_read_b128 v[170:173], v213 offset:0
	v_exp_f32_e32 v118, v118
	v_exp_f32_e32 v119, v119
	s_waitcnt lgkmcnt(5)
	v_mfma_f32_32x32x16_bf16 v[134:149], v[154:157], v[10:13], v[134:149]
	ds_read_b128 v[154:157], v212 offset:23232
	ds_read_b128 v[174:177], v213 offset:2560
	v_add_f32_e32 v0, v0, v118
	v_add_f32_e32 v0, v0, v119
	s_waitcnt lgkmcnt(6)
	v_mfma_f32_32x32x16_bf16 v[134:149], v[158:161], v[14:17], v[134:149]
	ds_read_b128 v[158:161], v212 offset:23264
	ds_read_b128 v[178:181], v213 offset:5120
	v_exp_f32_e32 v120, v120
	v_exp_f32_e32 v121, v121
	s_waitcnt lgkmcnt(7)
	v_mfma_f32_32x32x16_bf16 v[134:149], v[162:165], v[18:21], v[134:149]
	ds_read_b128 v[162:165], v212 offset:23296
	ds_read_b128 v[182:185], v213 offset:7680
	v_add_f32_e32 v0, v0, v120
	v_add_f32_e32 v0, v0, v121
	s_waitcnt lgkmcnt(8)
	v_mfma_f32_32x32x16_bf16 v[134:149], v[166:169], v[22:25], v[134:149]
	ds_read_b128 v[166:169], v212 offset:23328
	v_exp_f32_e32 v122, v122
	v_exp_f32_e32 v123, v123
	v_add_f32_e32 v0, v0, v122
	s_waitcnt lgkmcnt(8)
	v_mfma_f32_32x32x16_bf16 v[134:149], v[150:153], v[26:29], v[134:149]
	ds_read_b128 v[150:153], v212 offset:23360
	v_add_f32_e32 v0, v0, v123
	v_exp_f32_e32 v124, v124
	v_exp_f32_e32 v125, v125
	s_waitcnt lgkmcnt(7)
	v_mfma_f32_32x32x16_bf16 v[134:149], v[154:157], v[30:33], v[134:149]
	ds_read_b128 v[154:157], v212 offset:23392
	s_waitcnt vmcnt(9)
	ds_write_b128 v244, v[188:191] offset:46080
	global_load_dwordx4 v[188:191], v248, s[56:57]
	v_add_f32_e32 v0, v0, v124
	v_add_f32_e32 v0, v0, v125
	v_cvt_pk_bf16_f32 v118, v118, v119
	s_waitcnt lgkmcnt(7)
	v_mfma_f32_32x32x16_bf16 v[134:149], v[158:161], v[34:37], v[134:149]
	s_waitcnt vmcnt(9)
	ds_write_b128 v245, v[192:195] offset:46080
	global_load_dwordx4 v[192:195], v248, s[98:99] offset:-4096
	v_cvt_pk_bf16_f32 v119, v120, v121
	v_cvt_pk_bf16_f32 v120, v122, v123
	v_cvt_pk_bf16_f32 v121, v124, v125
	s_waitcnt lgkmcnt(6)
	v_mfma_f32_32x32x16_bf16 v[134:149], v[162:165], v[38:41], v[134:149]
	s_waitcnt vmcnt(9)
	ds_write_b128 v246, v[196:199] offset:46080
	global_load_dwordx4 v[196:199], v248, s[98:99]
	v_exp_f32_e32 v126, v126
	v_exp_f32_e32 v127, v127
	v_add_f32_e32 v0, v0, v126
	s_waitcnt lgkmcnt(5)
	v_mfma_f32_32x32x16_bf16 v[134:149], v[166:169], v[42:45], v[134:149]
	s_waitcnt vmcnt(9)
	ds_write_b128 v247, v[200:203] offset:46080
	global_load_dwordx4 v[200:203], v235, s[52:53]
	v_add_f32_e32 v0, v0, v127
	v_exp_f32_e32 v128, v128
	v_exp_f32_e32 v129, v129
	s_waitcnt lgkmcnt(5)
	v_mfma_f32_32x32x16_bf16 v[134:149], v[150:153], v[46:49], v[134:149]
	s_waitcnt vmcnt(9)
	ds_write_b128 v247, v[204:207] offset:51200
	global_load_dwordx4 v[204:207], v235, s[100:101]
	v_add_f32_e32 v0, v0, v128
	v_add_f32_e32 v0, v0, v129
	v_exp_f32_e32 v130, v130
	s_waitcnt lgkmcnt(5)
	v_mfma_f32_32x32x16_bf16 v[134:149], v[154:157], v[50:53], v[134:149]
	v_exp_f32_e32 v131, v131
	v_add_f32_e32 v0, v0, v130
	v_add_f32_e32 v0, v0, v131
	v_mfma_f32_32x32x16_bf16 v[54:69], v[170:173], v[118:121], v[54:69]
	ds_read_b128 v[170:173], v213 offset:32
	v_exp_f32_e32 v132, v132
	v_exp_f32_e32 v133, v133
	v_mfma_f32_32x32x16_bf16 v[70:85], v[174:177], v[118:121], v[70:85]
	ds_read_b128 v[174:177], v213 offset:2592
	v_add_f32_e32 v0, v0, v132
	v_add_f32_e32 v0, v0, v133
	v_mfma_f32_32x32x16_bf16 v[86:101], v[178:181], v[118:121], v[86:101]
	ds_read_b128 v[178:181], v213 offset:5152
	v_cvt_pk_bf16_f32 v126, v126, v127
	v_cvt_pk_bf16_f32 v127, v128, v129
	v_mfma_f32_32x32x16_bf16 v[102:117], v[182:185], v[118:121], v[102:117]
	ds_read_b128 v[182:185], v213 offset:7712
	v_cvt_pk_bf16_f32 v128, v130, v131
	v_cvt_pk_bf16_f32 v129, v132, v133
	s_waitcnt lgkmcnt(3)
	s_nop 1
	v_mfma_f32_32x32x16_bf16 v[54:69], v[170:173], v[126:129], v[54:69]
	s_add_u32 s56, s56, 0x3000
	s_addc_u32 s57, s57, 0
	s_waitcnt lgkmcnt(2)
	v_mfma_f32_32x32x16_bf16 v[70:85], v[174:177], v[126:129], v[70:85]
	s_add_u32 s98, s98, 0x3000
	s_addc_u32 s99, s99, 0
	s_waitcnt lgkmcnt(1)
	v_mfma_f32_32x32x16_bf16 v[86:101], v[178:181], v[126:129], v[86:101]
	s_add_u32 s52, s52, 64
	s_addc_u32 s53, s53, 0
	s_waitcnt lgkmcnt(0)
	v_mfma_f32_32x32x16_bf16 v[102:117], v[182:185], v[126:129], v[102:117]
	s_add_u32 s100, s100, 64
	s_addc_u32 s101, s101, 0
	s_waitcnt lgkmcnt(0)
	s_barrier
	ds_read_b128 v[150:153], v212 offset:46080
	ds_read_b128 v[154:157], v212 offset:46112
	ds_read_b128 v[158:161], v212 offset:46144
	ds_read_b128 v[162:165], v212 offset:46176
	ds_read_b128 v[166:169], v212 offset:46208
	s_waitcnt lgkmcnt(4)
	v_mfma_f32_32x32x16_bf16 v[118:133], v[150:153], v[6:9], 0
	ds_read_b128 v[150:153], v212 offset:46240
	ds_read_b128 v[170:173], v213 offset:23040
	v_exp_f32_e32 v134, v134
	v_exp_f32_e32 v135, v135
	s_waitcnt lgkmcnt(5)
	v_mfma_f32_32x32x16_bf16 v[118:133], v[154:157], v[10:13], v[118:133]
	ds_read_b128 v[154:157], v212 offset:46272
	ds_read_b128 v[174:177], v213 offset:25600
	v_add_f32_e32 v0, v0, v134
	v_add_f32_e32 v0, v0, v135
	s_waitcnt lgkmcnt(6)
	v_mfma_f32_32x32x16_bf16 v[118:133], v[158:161], v[14:17], v[118:133]
	ds_read_b128 v[158:161], v212 offset:46304
	ds_read_b128 v[178:181], v213 offset:28160
	v_exp_f32_e32 v136, v136
	v_exp_f32_e32 v137, v137
	s_waitcnt lgkmcnt(7)
	v_mfma_f32_32x32x16_bf16 v[118:133], v[162:165], v[18:21], v[118:133]
	ds_read_b128 v[162:165], v212 offset:46336
	ds_read_b128 v[182:185], v213 offset:30720
	v_add_f32_e32 v0, v0, v136
	v_add_f32_e32 v0, v0, v137
	s_waitcnt lgkmcnt(8)
	v_mfma_f32_32x32x16_bf16 v[118:133], v[166:169], v[22:25], v[118:133]
	ds_read_b128 v[166:169], v212 offset:46368
	v_exp_f32_e32 v138, v138
	v_exp_f32_e32 v139, v139
	v_add_f32_e32 v0, v0, v138
	s_waitcnt lgkmcnt(8)
	v_mfma_f32_32x32x16_bf16 v[118:133], v[150:153], v[26:29], v[118:133]
	ds_read_b128 v[150:153], v212 offset:46400
	v_add_f32_e32 v0, v0, v139
	v_exp_f32_e32 v140, v140
	v_exp_f32_e32 v141, v141
	s_waitcnt lgkmcnt(7)
	v_mfma_f32_32x32x16_bf16 v[118:133], v[154:157], v[30:33], v[118:133]
	ds_read_b128 v[154:157], v212 offset:46432
	s_waitcnt vmcnt(9)
	ds_write_b128 v244, v[208:211] offset:0
	global_load_dwordx4 v[208:211], v248, s[56:57]
	v_add_f32_e32 v0, v0, v140
	v_add_f32_e32 v0, v0, v141
	v_cvt_pk_bf16_f32 v134, v134, v135
	s_waitcnt lgkmcnt(7)
	v_mfma_f32_32x32x16_bf16 v[118:133], v[158:161], v[34:37], v[118:133]
	s_waitcnt vmcnt(9)
	ds_write_b128 v245, v[216:219] offset:0
	global_load_dwordx4 v[216:219], v248, s[98:99] offset:-4096
	v_cvt_pk_bf16_f32 v135, v136, v137
	v_cvt_pk_bf16_f32 v136, v138, v139
	v_cvt_pk_bf16_f32 v137, v140, v141
	s_waitcnt lgkmcnt(6)
	v_mfma_f32_32x32x16_bf16 v[118:133], v[162:165], v[38:41], v[118:133]
	s_waitcnt vmcnt(9)
	ds_write_b128 v246, v[220:223] offset:0
	global_load_dwordx4 v[220:223], v248, s[98:99]
	v_exp_f32_e32 v142, v142
	v_exp_f32_e32 v143, v143
	v_add_f32_e32 v0, v0, v142
	s_waitcnt lgkmcnt(5)
	v_mfma_f32_32x32x16_bf16 v[118:133], v[166:169], v[42:45], v[118:133]
	s_waitcnt vmcnt(9)
	ds_write_b128 v247, v[236:239] offset:0
	global_load_dwordx4 v[236:239], v235, s[52:53]
	v_add_f32_e32 v0, v0, v143
	v_exp_f32_e32 v144, v144
	v_exp_f32_e32 v145, v145
	s_waitcnt lgkmcnt(5)
	v_mfma_f32_32x32x16_bf16 v[118:133], v[150:153], v[46:49], v[118:133]
	s_waitcnt vmcnt(9)
	ds_write_b128 v247, v[240:243] offset:5120
	global_load_dwordx4 v[240:243], v235, s[100:101]
	v_add_f32_e32 v0, v0, v144
	v_add_f32_e32 v0, v0, v145
	v_exp_f32_e32 v146, v146
	s_waitcnt lgkmcnt(5)
	v_mfma_f32_32x32x16_bf16 v[118:133], v[154:157], v[50:53], v[118:133]
	v_exp_f32_e32 v147, v147
	v_add_f32_e32 v0, v0, v146
	v_add_f32_e32 v0, v0, v147
	v_mfma_f32_32x32x16_bf16 v[54:69], v[170:173], v[134:137], v[54:69]
	ds_read_b128 v[170:173], v213 offset:23072
	v_exp_f32_e32 v148, v148
	v_exp_f32_e32 v149, v149
	v_mfma_f32_32x32x16_bf16 v[70:85], v[174:177], v[134:137], v[70:85]
	ds_read_b128 v[174:177], v213 offset:25632
	v_add_f32_e32 v0, v0, v148
	v_add_f32_e32 v0, v0, v149
	v_mfma_f32_32x32x16_bf16 v[86:101], v[178:181], v[134:137], v[86:101]
	ds_read_b128 v[178:181], v213 offset:28192
	v_cvt_pk_bf16_f32 v142, v142, v143
	v_cvt_pk_bf16_f32 v143, v144, v145
	v_mfma_f32_32x32x16_bf16 v[102:117], v[182:185], v[134:137], v[102:117]
	ds_read_b128 v[182:185], v213 offset:30752
	v_cvt_pk_bf16_f32 v144, v146, v147
	v_cvt_pk_bf16_f32 v145, v148, v149
	s_waitcnt lgkmcnt(3)
	s_nop 1
	v_mfma_f32_32x32x16_bf16 v[54:69], v[170:173], v[142:145], v[54:69]
	s_add_u32 s56, s56, 0x3000
	s_addc_u32 s57, s57, 0
	s_waitcnt lgkmcnt(2)
	v_mfma_f32_32x32x16_bf16 v[70:85], v[174:177], v[142:145], v[70:85]
	s_add_u32 s98, s98, 0x3000
	s_addc_u32 s99, s99, 0
	s_waitcnt lgkmcnt(1)
	v_mfma_f32_32x32x16_bf16 v[86:101], v[178:181], v[142:145], v[86:101]
	s_add_u32 s52, s52, 64
	s_addc_u32 s53, s53, 0
	s_waitcnt lgkmcnt(0)
	v_mfma_f32_32x32x16_bf16 v[102:117], v[182:185], v[142:145], v[102:117]
	s_add_u32 s100, s100, 64
	s_addc_u32 s101, s101, 0
	s_waitcnt lgkmcnt(0)
	s_barrier
	ds_read_b128 v[150:153], v212 offset:0
	ds_read_b128 v[154:157], v212 offset:32
	ds_read_b128 v[158:161], v212 offset:64
	ds_read_b128 v[162:165], v212 offset:96
	ds_read_b128 v[166:169], v212 offset:128
	s_waitcnt lgkmcnt(4)
	v_mfma_f32_32x32x16_bf16 v[134:149], v[150:153], v[6:9], 0
	ds_read_b128 v[150:153], v212 offset:160
	ds_read_b128 v[170:173], v213 offset:46080
	v_exp_f32_e32 v118, v118
	v_exp_f32_e32 v119, v119
	s_waitcnt lgkmcnt(5)
	v_mfma_f32_32x32x16_bf16 v[134:149], v[154:157], v[10:13], v[134:149]
	ds_read_b128 v[154:157], v212 offset:192
	ds_read_b128 v[174:177], v213 offset:48640
	v_add_f32_e32 v0, v0, v118
	v_add_f32_e32 v0, v0, v119
	s_waitcnt lgkmcnt(6)
	v_mfma_f32_32x32x16_bf16 v[134:149], v[158:161], v[14:17], v[134:149]
	ds_read_b128 v[158:161], v212 offset:224
	ds_read_b128 v[178:181], v213 offset:51200
	v_exp_f32_e32 v120, v120
	v_exp_f32_e32 v121, v121
	s_waitcnt lgkmcnt(7)
	v_mfma_f32_32x32x16_bf16 v[134:149], v[162:165], v[18:21], v[134:149]
	ds_read_b128 v[162:165], v212 offset:256
	ds_read_b128 v[182:185], v213 offset:53760
	v_add_f32_e32 v0, v0, v120
	v_add_f32_e32 v0, v0, v121
	s_waitcnt lgkmcnt(8)
	v_mfma_f32_32x32x16_bf16 v[134:149], v[166:169], v[22:25], v[134:149]
	ds_read_b128 v[166:169], v212 offset:288
	v_exp_f32_e32 v122, v122
	v_exp_f32_e32 v123, v123
	v_add_f32_e32 v0, v0, v122
	s_waitcnt lgkmcnt(8)
	v_mfma_f32_32x32x16_bf16 v[134:149], v[150:153], v[26:29], v[134:149]
	ds_read_b128 v[150:153], v212 offset:320
	v_add_f32_e32 v0, v0, v123
	v_exp_f32_e32 v124, v124
	v_exp_f32_e32 v125, v125
	s_waitcnt lgkmcnt(7)
	v_mfma_f32_32x32x16_bf16 v[134:149], v[154:157], v[30:33], v[134:149]
	ds_read_b128 v[154:157], v212 offset:352
	s_waitcnt vmcnt(9)
	ds_write_b128 v244, v[188:191] offset:23040
	global_load_dwordx4 v[188:191], v248, s[56:57]
	v_add_f32_e32 v0, v0, v124
	v_add_f32_e32 v0, v0, v125
	v_cvt_pk_bf16_f32 v118, v118, v119
	s_waitcnt lgkmcnt(7)
	v_mfma_f32_32x32x16_bf16 v[134:149], v[158:161], v[34:37], v[134:149]
	s_waitcnt vmcnt(9)
	ds_write_b128 v245, v[192:195] offset:23040
	global_load_dwordx4 v[192:195], v248, s[98:99] offset:-4096
	v_cvt_pk_bf16_f32 v119, v120, v121
	v_cvt_pk_bf16_f32 v120, v122, v123
	v_cvt_pk_bf16_f32 v121, v124, v125
	s_waitcnt lgkmcnt(6)
	v_mfma_f32_32x32x16_bf16 v[134:149], v[162:165], v[38:41], v[134:149]
	s_waitcnt vmcnt(9)
	ds_write_b128 v246, v[196:199] offset:23040
	global_load_dwordx4 v[196:199], v248, s[98:99]
	v_exp_f32_e32 v126, v126
	v_exp_f32_e32 v127, v127
	v_add_f32_e32 v0, v0, v126
	s_waitcnt lgkmcnt(5)
	v_mfma_f32_32x32x16_bf16 v[134:149], v[166:169], v[42:45], v[134:149]
	s_waitcnt vmcnt(9)
	ds_write_b128 v247, v[200:203] offset:23040
	global_load_dwordx4 v[200:203], v235, s[52:53]
	v_add_f32_e32 v0, v0, v127
	v_exp_f32_e32 v128, v128
	v_exp_f32_e32 v129, v129
	s_waitcnt lgkmcnt(5)
	v_mfma_f32_32x32x16_bf16 v[134:149], v[150:153], v[46:49], v[134:149]
	s_waitcnt vmcnt(9)
	ds_write_b128 v247, v[204:207] offset:28160
	global_load_dwordx4 v[204:207], v235, s[100:101]
	v_add_f32_e32 v0, v0, v128
	v_add_f32_e32 v0, v0, v129
	v_exp_f32_e32 v130, v130
	s_waitcnt lgkmcnt(5)
	v_mfma_f32_32x32x16_bf16 v[134:149], v[154:157], v[50:53], v[134:149]
	v_exp_f32_e32 v131, v131
	v_add_f32_e32 v0, v0, v130
	v_add_f32_e32 v0, v0, v131
	v_mfma_f32_32x32x16_bf16 v[54:69], v[170:173], v[118:121], v[54:69]
	ds_read_b128 v[170:173], v213 offset:46112
	v_exp_f32_e32 v132, v132
	v_exp_f32_e32 v133, v133
	v_mfma_f32_32x32x16_bf16 v[70:85], v[174:177], v[118:121], v[70:85]
	ds_read_b128 v[174:177], v213 offset:48672
	v_add_f32_e32 v0, v0, v132
	v_add_f32_e32 v0, v0, v133
	v_mfma_f32_32x32x16_bf16 v[86:101], v[178:181], v[118:121], v[86:101]
	ds_read_b128 v[178:181], v213 offset:51232
	v_cvt_pk_bf16_f32 v126, v126, v127
	v_cvt_pk_bf16_f32 v127, v128, v129
	v_mfma_f32_32x32x16_bf16 v[102:117], v[182:185], v[118:121], v[102:117]
	ds_read_b128 v[182:185], v213 offset:53792
	v_cvt_pk_bf16_f32 v128, v130, v131
	v_cvt_pk_bf16_f32 v129, v132, v133
	s_waitcnt lgkmcnt(3)
	s_nop 1
	v_mfma_f32_32x32x16_bf16 v[54:69], v[170:173], v[126:129], v[54:69]
	s_add_u32 s56, s56, 0x3000
	s_addc_u32 s57, s57, 0
	s_waitcnt lgkmcnt(2)
	v_mfma_f32_32x32x16_bf16 v[70:85], v[174:177], v[126:129], v[70:85]
	s_add_u32 s98, s98, 0x3000
	s_addc_u32 s99, s99, 0
	s_waitcnt lgkmcnt(1)
	v_mfma_f32_32x32x16_bf16 v[86:101], v[178:181], v[126:129], v[86:101]
	s_add_u32 s52, s52, 64
	s_addc_u32 s53, s53, 0
	s_waitcnt lgkmcnt(0)
	v_mfma_f32_32x32x16_bf16 v[102:117], v[182:185], v[126:129], v[102:117]
	s_add_u32 s100, s100, 64
	s_addc_u32 s101, s101, 0
	s_waitcnt lgkmcnt(0)
	s_barrier
	ds_read_b128 v[150:153], v212 offset:23040
	ds_read_b128 v[154:157], v212 offset:23072
	ds_read_b128 v[158:161], v212 offset:23104
	ds_read_b128 v[162:165], v212 offset:23136
	ds_read_b128 v[166:169], v212 offset:23168
	s_waitcnt lgkmcnt(4)
	v_mfma_f32_32x32x16_bf16 v[118:133], v[150:153], v[6:9], 0
	ds_read_b128 v[150:153], v212 offset:23200
	ds_read_b128 v[170:173], v213 offset:0
	v_exp_f32_e32 v134, v134
	v_exp_f32_e32 v135, v135
	s_waitcnt lgkmcnt(5)
	v_mfma_f32_32x32x16_bf16 v[118:133], v[154:157], v[10:13], v[118:133]
	ds_read_b128 v[154:157], v212 offset:23232
	ds_read_b128 v[174:177], v213 offset:2560
	v_add_f32_e32 v0, v0, v134
	v_add_f32_e32 v0, v0, v135
	s_waitcnt lgkmcnt(6)
	v_mfma_f32_32x32x16_bf16 v[118:133], v[158:161], v[14:17], v[118:133]
	ds_read_b128 v[158:161], v212 offset:23264
	ds_read_b128 v[178:181], v213 offset:5120
	v_exp_f32_e32 v136, v136
	v_exp_f32_e32 v137, v137
	s_waitcnt lgkmcnt(7)
	v_mfma_f32_32x32x16_bf16 v[118:133], v[162:165], v[18:21], v[118:133]
	ds_read_b128 v[162:165], v212 offset:23296
	ds_read_b128 v[182:185], v213 offset:7680
	v_add_f32_e32 v0, v0, v136
	v_add_f32_e32 v0, v0, v137
	s_waitcnt lgkmcnt(8)
	v_mfma_f32_32x32x16_bf16 v[118:133], v[166:169], v[22:25], v[118:133]
	ds_read_b128 v[166:169], v212 offset:23328
	v_exp_f32_e32 v138, v138
	v_exp_f32_e32 v139, v139
	v_add_f32_e32 v0, v0, v138
	s_waitcnt lgkmcnt(8)
	v_mfma_f32_32x32x16_bf16 v[118:133], v[150:153], v[26:29], v[118:133]
	ds_read_b128 v[150:153], v212 offset:23360
	v_add_f32_e32 v0, v0, v139
	v_exp_f32_e32 v140, v140
	v_exp_f32_e32 v141, v141
	s_waitcnt lgkmcnt(7)
	v_mfma_f32_32x32x16_bf16 v[118:133], v[154:157], v[30:33], v[118:133]
	ds_read_b128 v[154:157], v212 offset:23392
	s_waitcnt vmcnt(9)
	ds_write_b128 v244, v[208:211] offset:46080
	global_load_dwordx4 v[208:211], v248, s[56:57]
	v_add_f32_e32 v0, v0, v140
	v_add_f32_e32 v0, v0, v141
	v_cvt_pk_bf16_f32 v134, v134, v135
	s_waitcnt lgkmcnt(7)
	v_mfma_f32_32x32x16_bf16 v[118:133], v[158:161], v[34:37], v[118:133]
	s_waitcnt vmcnt(9)
	ds_write_b128 v245, v[216:219] offset:46080
	global_load_dwordx4 v[216:219], v248, s[98:99] offset:-4096
	v_cvt_pk_bf16_f32 v135, v136, v137
	v_cvt_pk_bf16_f32 v136, v138, v139
	v_cvt_pk_bf16_f32 v137, v140, v141
	s_waitcnt lgkmcnt(6)
	v_mfma_f32_32x32x16_bf16 v[118:133], v[162:165], v[38:41], v[118:133]
	s_waitcnt vmcnt(9)
	ds_write_b128 v246, v[220:223] offset:46080
	global_load_dwordx4 v[220:223], v248, s[98:99]
	v_exp_f32_e32 v142, v142
	v_exp_f32_e32 v143, v143
	v_add_f32_e32 v0, v0, v142
	s_waitcnt lgkmcnt(5)
	v_mfma_f32_32x32x16_bf16 v[118:133], v[166:169], v[42:45], v[118:133]
	s_waitcnt vmcnt(9)
	ds_write_b128 v247, v[236:239] offset:46080
	global_load_dwordx4 v[236:239], v235, s[52:53]
	v_add_f32_e32 v0, v0, v143
	v_exp_f32_e32 v144, v144
	v_exp_f32_e32 v145, v145
	s_waitcnt lgkmcnt(5)
	v_mfma_f32_32x32x16_bf16 v[118:133], v[150:153], v[46:49], v[118:133]
	s_waitcnt vmcnt(9)
	ds_write_b128 v247, v[240:243] offset:51200
	global_load_dwordx4 v[240:243], v235, s[100:101]
	v_add_f32_e32 v0, v0, v144
	v_add_f32_e32 v0, v0, v145
	v_exp_f32_e32 v146, v146
	s_waitcnt lgkmcnt(5)
	v_mfma_f32_32x32x16_bf16 v[118:133], v[154:157], v[50:53], v[118:133]
	v_exp_f32_e32 v147, v147
	v_add_f32_e32 v0, v0, v146
	v_add_f32_e32 v0, v0, v147
	v_mfma_f32_32x32x16_bf16 v[54:69], v[170:173], v[134:137], v[54:69]
	ds_read_b128 v[170:173], v213 offset:32
	v_exp_f32_e32 v148, v148
	v_exp_f32_e32 v149, v149
	v_mfma_f32_32x32x16_bf16 v[70:85], v[174:177], v[134:137], v[70:85]
	ds_read_b128 v[174:177], v213 offset:2592
	v_add_f32_e32 v0, v0, v148
	v_add_f32_e32 v0, v0, v149
	v_mfma_f32_32x32x16_bf16 v[86:101], v[178:181], v[134:137], v[86:101]
	ds_read_b128 v[178:181], v213 offset:5152
	v_cvt_pk_bf16_f32 v142, v142, v143
	v_cvt_pk_bf16_f32 v143, v144, v145
	v_mfma_f32_32x32x16_bf16 v[102:117], v[182:185], v[134:137], v[102:117]
	ds_read_b128 v[182:185], v213 offset:7712
	v_cvt_pk_bf16_f32 v144, v146, v147
	v_cvt_pk_bf16_f32 v145, v148, v149
	s_waitcnt lgkmcnt(3)
	s_nop 1
	v_mfma_f32_32x32x16_bf16 v[54:69], v[170:173], v[142:145], v[54:69]
	s_add_u32 s56, s56, 0x3000
	s_addc_u32 s57, s57, 0
	s_waitcnt lgkmcnt(2)
	v_mfma_f32_32x32x16_bf16 v[70:85], v[174:177], v[142:145], v[70:85]
	s_add_u32 s98, s98, 0x3000
	s_addc_u32 s99, s99, 0
	s_waitcnt lgkmcnt(1)
	v_mfma_f32_32x32x16_bf16 v[86:101], v[178:181], v[142:145], v[86:101]
	s_add_u32 s52, s52, 64
	s_addc_u32 s53, s53, 0
	s_waitcnt lgkmcnt(0)
	v_mfma_f32_32x32x16_bf16 v[102:117], v[182:185], v[142:145], v[102:117]
	s_add_u32 s100, s100, 64
	s_addc_u32 s101, s101, 0
	s_waitcnt lgkmcnt(0)
	s_barrier
	ds_read_b128 v[150:153], v212 offset:46080
	ds_read_b128 v[154:157], v212 offset:46112
	ds_read_b128 v[158:161], v212 offset:46144
	ds_read_b128 v[162:165], v212 offset:46176
	ds_read_b128 v[166:169], v212 offset:46208
	s_waitcnt lgkmcnt(4)
	v_mfma_f32_32x32x16_bf16 v[134:149], v[150:153], v[6:9], 0
	ds_read_b128 v[150:153], v212 offset:46240
	ds_read_b128 v[170:173], v213 offset:23040
	v_exp_f32_e32 v118, v118
	v_exp_f32_e32 v119, v119
	s_waitcnt lgkmcnt(5)
	v_mfma_f32_32x32x16_bf16 v[134:149], v[154:157], v[10:13], v[134:149]
	ds_read_b128 v[154:157], v212 offset:46272
	ds_read_b128 v[174:177], v213 offset:25600
	v_add_f32_e32 v0, v0, v118
	v_add_f32_e32 v0, v0, v119
	s_waitcnt lgkmcnt(6)
	v_mfma_f32_32x32x16_bf16 v[134:149], v[158:161], v[14:17], v[134:149]
	ds_read_b128 v[158:161], v212 offset:46304
	ds_read_b128 v[178:181], v213 offset:28160
	v_exp_f32_e32 v120, v120
	v_exp_f32_e32 v121, v121
	s_waitcnt lgkmcnt(7)
	v_mfma_f32_32x32x16_bf16 v[134:149], v[162:165], v[18:21], v[134:149]
	ds_read_b128 v[162:165], v212 offset:46336
	ds_read_b128 v[182:185], v213 offset:30720
	v_add_f32_e32 v0, v0, v120
	v_add_f32_e32 v0, v0, v121
	s_waitcnt lgkmcnt(8)
	v_mfma_f32_32x32x16_bf16 v[134:149], v[166:169], v[22:25], v[134:149]
	ds_read_b128 v[166:169], v212 offset:46368
	v_exp_f32_e32 v122, v122
	v_exp_f32_e32 v123, v123
	v_add_f32_e32 v0, v0, v122
	s_waitcnt lgkmcnt(8)
	v_mfma_f32_32x32x16_bf16 v[134:149], v[150:153], v[26:29], v[134:149]
	ds_read_b128 v[150:153], v212 offset:46400
	v_add_f32_e32 v0, v0, v123
	v_exp_f32_e32 v124, v124
	v_exp_f32_e32 v125, v125
	s_waitcnt lgkmcnt(7)
	v_mfma_f32_32x32x16_bf16 v[134:149], v[154:157], v[30:33], v[134:149]
	ds_read_b128 v[154:157], v212 offset:46432
	s_waitcnt vmcnt(9)
	ds_write_b128 v244, v[188:191] offset:0
	global_load_dwordx4 v[188:191], v248, s[56:57]
	v_add_f32_e32 v0, v0, v124
	v_add_f32_e32 v0, v0, v125
	v_cvt_pk_bf16_f32 v118, v118, v119
	s_waitcnt lgkmcnt(7)
	v_mfma_f32_32x32x16_bf16 v[134:149], v[158:161], v[34:37], v[134:149]
	s_waitcnt vmcnt(9)
	ds_write_b128 v245, v[192:195] offset:0
	global_load_dwordx4 v[192:195], v248, s[98:99] offset:-4096
	v_cvt_pk_bf16_f32 v119, v120, v121
	v_cvt_pk_bf16_f32 v120, v122, v123
	v_cvt_pk_bf16_f32 v121, v124, v125
	s_waitcnt lgkmcnt(6)
	v_mfma_f32_32x32x16_bf16 v[134:149], v[162:165], v[38:41], v[134:149]
	s_waitcnt vmcnt(9)
	ds_write_b128 v246, v[196:199] offset:0
	global_load_dwordx4 v[196:199], v248, s[98:99]
	v_exp_f32_e32 v126, v126
	v_exp_f32_e32 v127, v127
	v_add_f32_e32 v0, v0, v126
	s_waitcnt lgkmcnt(5)
	v_mfma_f32_32x32x16_bf16 v[134:149], v[166:169], v[42:45], v[134:149]
	s_waitcnt vmcnt(9)
	ds_write_b128 v247, v[200:203] offset:0
	global_load_dwordx4 v[200:203], v235, s[52:53]
	v_add_f32_e32 v0, v0, v127
	v_exp_f32_e32 v128, v128
	v_exp_f32_e32 v129, v129
	s_waitcnt lgkmcnt(5)
	v_mfma_f32_32x32x16_bf16 v[134:149], v[150:153], v[46:49], v[134:149]
	s_waitcnt vmcnt(9)
	ds_write_b128 v247, v[204:207] offset:5120
	global_load_dwordx4 v[204:207], v235, s[100:101]
	v_add_f32_e32 v0, v0, v128
	v_add_f32_e32 v0, v0, v129
	v_exp_f32_e32 v130, v130
	s_waitcnt lgkmcnt(5)
	v_mfma_f32_32x32x16_bf16 v[134:149], v[154:157], v[50:53], v[134:149]
	v_exp_f32_e32 v131, v131
	v_add_f32_e32 v0, v0, v130
	v_add_f32_e32 v0, v0, v131
	v_mfma_f32_32x32x16_bf16 v[54:69], v[170:173], v[118:121], v[54:69]
	ds_read_b128 v[170:173], v213 offset:23072
	v_exp_f32_e32 v132, v132
	v_exp_f32_e32 v133, v133
	v_mfma_f32_32x32x16_bf16 v[70:85], v[174:177], v[118:121], v[70:85]
	ds_read_b128 v[174:177], v213 offset:25632
	v_add_f32_e32 v0, v0, v132
	v_add_f32_e32 v0, v0, v133
	v_mfma_f32_32x32x16_bf16 v[86:101], v[178:181], v[118:121], v[86:101]
	ds_read_b128 v[178:181], v213 offset:28192
	v_cvt_pk_bf16_f32 v126, v126, v127
	v_cvt_pk_bf16_f32 v127, v128, v129
	v_mfma_f32_32x32x16_bf16 v[102:117], v[182:185], v[118:121], v[102:117]
	ds_read_b128 v[182:185], v213 offset:30752
	v_cvt_pk_bf16_f32 v128, v130, v131
	v_cvt_pk_bf16_f32 v129, v132, v133
	s_waitcnt lgkmcnt(3)
	s_nop 1
	v_mfma_f32_32x32x16_bf16 v[54:69], v[170:173], v[126:129], v[54:69]
	s_add_u32 s56, s56, 0x3000
	s_addc_u32 s57, s57, 0
	s_waitcnt lgkmcnt(2)
	v_mfma_f32_32x32x16_bf16 v[70:85], v[174:177], v[126:129], v[70:85]
	s_add_u32 s98, s98, 0x3000
	s_addc_u32 s99, s99, 0
	s_waitcnt lgkmcnt(1)
	v_mfma_f32_32x32x16_bf16 v[86:101], v[178:181], v[126:129], v[86:101]
	s_add_u32 s52, s52, 64
	s_addc_u32 s53, s53, 0
	s_waitcnt lgkmcnt(0)
	v_mfma_f32_32x32x16_bf16 v[102:117], v[182:185], v[126:129], v[102:117]
	s_add_u32 s100, s100, 64
	s_addc_u32 s101, s101, 0
	s_waitcnt lgkmcnt(0)
	s_barrier
	ds_read_b128 v[150:153], v212 offset:0
	ds_read_b128 v[154:157], v212 offset:32
	ds_read_b128 v[158:161], v212 offset:64
	ds_read_b128 v[162:165], v212 offset:96
	ds_read_b128 v[166:169], v212 offset:128
	s_waitcnt lgkmcnt(4)
	v_mfma_f32_32x32x16_bf16 v[118:133], v[150:153], v[6:9], 0
	ds_read_b128 v[150:153], v212 offset:160
	ds_read_b128 v[170:173], v213 offset:46080
	v_exp_f32_e32 v134, v134
	v_exp_f32_e32 v135, v135
	s_waitcnt lgkmcnt(5)
	v_mfma_f32_32x32x16_bf16 v[118:133], v[154:157], v[10:13], v[118:133]
	ds_read_b128 v[154:157], v212 offset:192
	ds_read_b128 v[174:177], v213 offset:48640
	v_add_f32_e32 v0, v0, v134
	v_add_f32_e32 v0, v0, v135
	s_waitcnt lgkmcnt(6)
	v_mfma_f32_32x32x16_bf16 v[118:133], v[158:161], v[14:17], v[118:133]
	ds_read_b128 v[158:161], v212 offset:224
	ds_read_b128 v[178:181], v213 offset:51200
	v_exp_f32_e32 v136, v136
	v_exp_f32_e32 v137, v137
	s_waitcnt lgkmcnt(7)
	v_mfma_f32_32x32x16_bf16 v[118:133], v[162:165], v[18:21], v[118:133]
	ds_read_b128 v[162:165], v212 offset:256
	ds_read_b128 v[182:185], v213 offset:53760
	v_add_f32_e32 v0, v0, v136
	v_add_f32_e32 v0, v0, v137
	s_waitcnt lgkmcnt(8)
	v_mfma_f32_32x32x16_bf16 v[118:133], v[166:169], v[22:25], v[118:133]
	ds_read_b128 v[166:169], v212 offset:288
	v_exp_f32_e32 v138, v138
	v_exp_f32_e32 v139, v139
	v_add_f32_e32 v0, v0, v138
	s_waitcnt lgkmcnt(8)
	v_mfma_f32_32x32x16_bf16 v[118:133], v[150:153], v[26:29], v[118:133]
	ds_read_b128 v[150:153], v212 offset:320
	v_add_f32_e32 v0, v0, v139
	v_exp_f32_e32 v140, v140
	v_exp_f32_e32 v141, v141
	s_waitcnt lgkmcnt(7)
	v_mfma_f32_32x32x16_bf16 v[118:133], v[154:157], v[30:33], v[118:133]
	ds_read_b128 v[154:157], v212 offset:352
	s_waitcnt vmcnt(9)
	ds_write_b128 v244, v[208:211] offset:23040
	global_load_dwordx4 v[208:211], v248, s[56:57]
	v_add_f32_e32 v0, v0, v140
	v_add_f32_e32 v0, v0, v141
	v_cvt_pk_bf16_f32 v134, v134, v135
	s_waitcnt lgkmcnt(7)
	v_mfma_f32_32x32x16_bf16 v[118:133], v[158:161], v[34:37], v[118:133]
	s_waitcnt vmcnt(9)
	ds_write_b128 v245, v[216:219] offset:23040
	global_load_dwordx4 v[216:219], v248, s[98:99] offset:-4096
	v_cvt_pk_bf16_f32 v135, v136, v137
	v_cvt_pk_bf16_f32 v136, v138, v139
	v_cvt_pk_bf16_f32 v137, v140, v141
	s_waitcnt lgkmcnt(6)
	v_mfma_f32_32x32x16_bf16 v[118:133], v[162:165], v[38:41], v[118:133]
	s_waitcnt vmcnt(9)
	ds_write_b128 v246, v[220:223] offset:23040
	global_load_dwordx4 v[220:223], v248, s[98:99]
	v_exp_f32_e32 v142, v142
	v_exp_f32_e32 v143, v143
	v_add_f32_e32 v0, v0, v142
	s_waitcnt lgkmcnt(5)
	v_mfma_f32_32x32x16_bf16 v[118:133], v[166:169], v[42:45], v[118:133]
	s_waitcnt vmcnt(9)
	ds_write_b128 v247, v[236:239] offset:23040
	global_load_dwordx4 v[236:239], v235, s[52:53]
	v_add_f32_e32 v0, v0, v143
	v_exp_f32_e32 v144, v144
	v_exp_f32_e32 v145, v145
	s_waitcnt lgkmcnt(5)
	v_mfma_f32_32x32x16_bf16 v[118:133], v[150:153], v[46:49], v[118:133]
	s_waitcnt vmcnt(9)
	ds_write_b128 v247, v[240:243] offset:28160
	global_load_dwordx4 v[240:243], v235, s[100:101]
	v_add_f32_e32 v0, v0, v144
	v_add_f32_e32 v0, v0, v145
	v_exp_f32_e32 v146, v146
	s_waitcnt lgkmcnt(5)
	v_mfma_f32_32x32x16_bf16 v[118:133], v[154:157], v[50:53], v[118:133]
	v_exp_f32_e32 v147, v147
	v_add_f32_e32 v0, v0, v146
	v_add_f32_e32 v0, v0, v147
	v_mfma_f32_32x32x16_bf16 v[54:69], v[170:173], v[134:137], v[54:69]
	ds_read_b128 v[170:173], v213 offset:46112
	v_exp_f32_e32 v148, v148
	v_exp_f32_e32 v149, v149
	v_mfma_f32_32x32x16_bf16 v[70:85], v[174:177], v[134:137], v[70:85]
	ds_read_b128 v[174:177], v213 offset:48672
	v_add_f32_e32 v0, v0, v148
	v_add_f32_e32 v0, v0, v149
	v_mfma_f32_32x32x16_bf16 v[86:101], v[178:181], v[134:137], v[86:101]
	ds_read_b128 v[178:181], v213 offset:51232
	v_cvt_pk_bf16_f32 v142, v142, v143
	v_cvt_pk_bf16_f32 v143, v144, v145
	v_mfma_f32_32x32x16_bf16 v[102:117], v[182:185], v[134:137], v[102:117]
	ds_read_b128 v[182:185], v213 offset:53792
	v_cvt_pk_bf16_f32 v144, v146, v147
	v_cvt_pk_bf16_f32 v145, v148, v149
	s_waitcnt lgkmcnt(3)
	s_nop 1
	v_mfma_f32_32x32x16_bf16 v[54:69], v[170:173], v[142:145], v[54:69]
	s_add_u32 s56, s56, 0x3000
	s_addc_u32 s57, s57, 0
	s_waitcnt lgkmcnt(2)
	v_mfma_f32_32x32x16_bf16 v[70:85], v[174:177], v[142:145], v[70:85]
	s_add_u32 s98, s98, 0x3000
	s_addc_u32 s99, s99, 0
	s_waitcnt lgkmcnt(1)
	v_mfma_f32_32x32x16_bf16 v[86:101], v[178:181], v[142:145], v[86:101]
	s_add_u32 s52, s52, 64
	s_addc_u32 s53, s53, 0
	s_waitcnt lgkmcnt(0)
	v_mfma_f32_32x32x16_bf16 v[102:117], v[182:185], v[142:145], v[102:117]
	s_add_u32 s100, s100, 64
	s_addc_u32 s101, s101, 0
	s_waitcnt lgkmcnt(0)
	s_barrier
	s_sub_i32 s47, s47, 1
	s_cmp_lg_u32 s47, 0
	s_cbranch_scc1 .Lfa_loop
	ds_read_b128 v[150:153], v212 offset:23040
	ds_read_b128 v[154:157], v212 offset:23072
	ds_read_b128 v[158:161], v212 offset:23104
	ds_read_b128 v[162:165], v212 offset:23136
	ds_read_b128 v[166:169], v212 offset:23168
	s_waitcnt lgkmcnt(4)
	v_mfma_f32_32x32x16_bf16 v[134:149], v[150:153], v[6:9], 0
	ds_read_b128 v[150:153], v212 offset:23200
	ds_read_b128 v[170:173], v213 offset:0
	v_exp_f32_e32 v118, v118
	v_exp_f32_e32 v119, v119
	s_waitcnt lgkmcnt(5)
	v_mfma_f32_32x32x16_bf16 v[134:149], v[154:157], v[10:13], v[134:149]
	ds_read_b128 v[154:157], v212 offset:23232
	ds_read_b128 v[174:177], v213 offset:2560
	v_add_f32_e32 v0, v0, v118
	v_add_f32_e32 v0, v0, v119
	s_waitcnt lgkmcnt(6)
	v_mfma_f32_32x32x16_bf16 v[134:149], v[158:161], v[14:17], v[134:149]
	ds_read_b128 v[158:161], v212 offset:23264
	ds_read_b128 v[178:181], v213 offset:5120
	v_exp_f32_e32 v120, v120
	v_exp_f32_e32 v121, v121
	s_waitcnt lgkmcnt(7)
	v_mfma_f32_32x32x16_bf16 v[134:149], v[162:165], v[18:21], v[134:149]
	ds_read_b128 v[162:165], v212 offset:23296
	ds_read_b128 v[182:185], v213 offset:7680
	v_add_f32_e32 v0, v0, v120
	v_add_f32_e32 v0, v0, v121
	s_waitcnt lgkmcnt(8)
	v_mfma_f32_32x32x16_bf16 v[134:149], v[166:169], v[22:25], v[134:149]
	ds_read_b128 v[166:169], v212 offset:23328
	v_exp_f32_e32 v122, v122
	v_exp_f32_e32 v123, v123
	v_add_f32_e32 v0, v0, v122
	s_waitcnt lgkmcnt(8)
	v_mfma_f32_32x32x16_bf16 v[134:149], v[150:153], v[26:29], v[134:149]
	ds_read_b128 v[150:153], v212 offset:23360
	v_add_f32_e32 v0, v0, v123
	v_exp_f32_e32 v124, v124
	v_exp_f32_e32 v125, v125
	s_waitcnt lgkmcnt(7)
	v_mfma_f32_32x32x16_bf16 v[134:149], v[154:157], v[30:33], v[134:149]
	ds_read_b128 v[154:157], v212 offset:23392
	s_waitcnt vmcnt(9)
	ds_write_b128 v244, v[188:191] offset:46080
	global_load_dwordx4 v[188:191], v248, s[56:57]
	v_add_f32_e32 v0, v0, v124
	v_add_f32_e32 v0, v0, v125
	v_cvt_pk_bf16_f32 v118, v118, v119
	s_waitcnt lgkmcnt(7)
	v_mfma_f32_32x32x16_bf16 v[134:149], v[158:161], v[34:37], v[134:149]
	s_waitcnt vmcnt(9)
	ds_write_b128 v245, v[192:195] offset:46080
	global_load_dwordx4 v[192:195], v248, s[98:99] offset:-4096
	v_cvt_pk_bf16_f32 v119, v120, v121
	v_cvt_pk_bf16_f32 v120, v122, v123
	v_cvt_pk_bf16_f32 v121, v124, v125
	s_waitcnt lgkmcnt(6)
	v_mfma_f32_32x32x16_bf16 v[134:149], v[162:165], v[38:41], v[134:149]
	s_waitcnt vmcnt(9)
	ds_write_b128 v246, v[196:199] offset:46080
	global_load_dwordx4 v[196:199], v248, s[98:99]
	v_exp_f32_e32 v126, v126
	v_exp_f32_e32 v127, v127
	v_add_f32_e32 v0, v0, v126
	s_waitcnt lgkmcnt(5)
	v_mfma_f32_32x32x16_bf16 v[134:149], v[166:169], v[42:45], v[134:149]
	s_waitcnt vmcnt(9)
	ds_write_b128 v247, v[200:203] offset:46080
	global_load_dwordx4 v[200:203], v235, s[52:53]
	v_add_f32_e32 v0, v0, v127
	v_exp_f32_e32 v128, v128
	v_exp_f32_e32 v129, v129
	s_waitcnt lgkmcnt(5)
	v_mfma_f32_32x32x16_bf16 v[134:149], v[150:153], v[46:49], v[134:149]
	s_waitcnt vmcnt(9)
	ds_write_b128 v247, v[204:207] offset:51200
	global_load_dwordx4 v[204:207], v235, s[100:101]
	v_add_f32_e32 v0, v0, v128
	v_add_f32_e32 v0, v0, v129
	v_exp_f32_e32 v130, v130
	s_waitcnt lgkmcnt(5)
	v_mfma_f32_32x32x16_bf16 v[134:149], v[154:157], v[50:53], v[134:149]
	v_exp_f32_e32 v131, v131
	v_add_f32_e32 v0, v0, v130
	v_add_f32_e32 v0, v0, v131
	v_mfma_f32_32x32x16_bf16 v[54:69], v[170:173], v[118:121], v[54:69]
	ds_read_b128 v[170:173], v213 offset:32
	v_exp_f32_e32 v132, v132
	v_exp_f32_e32 v133, v133
	v_mfma_f32_32x32x16_bf16 v[70:85], v[174:177], v[118:121], v[70:85]
	ds_read_b128 v[174:177], v213 offset:2592
	v_add_f32_e32 v0, v0, v132
	v_add_f32_e32 v0, v0, v133
	v_mfma_f32_32x32x16_bf16 v[86:101], v[178:181], v[118:121], v[86:101]
	ds_read_b128 v[178:181], v213 offset:5152
	v_cvt_pk_bf16_f32 v126, v126, v127
	v_cvt_pk_bf16_f32 v127, v128, v129
	v_mfma_f32_32x32x16_bf16 v[102:117], v[182:185], v[118:121], v[102:117]
	ds_read_b128 v[182:185], v213 offset:7712
	v_cvt_pk_bf16_f32 v128, v130, v131
	v_cvt_pk_bf16_f32 v129, v132, v133
	s_waitcnt lgkmcnt(3)
	s_nop 1
	v_mfma_f32_32x32x16_bf16 v[54:69], v[170:173], v[126:129], v[54:69]
	s_add_u32 s56, s56, 0x3000
	s_addc_u32 s57, s57, 0
	s_waitcnt lgkmcnt(2)
	v_mfma_f32_32x32x16_bf16 v[70:85], v[174:177], v[126:129], v[70:85]
	s_add_u32 s98, s98, 0x3000
	s_addc_u32 s99, s99, 0
	s_waitcnt lgkmcnt(1)
	v_mfma_f32_32x32x16_bf16 v[86:101], v[178:181], v[126:129], v[86:101]
	s_add_u32 s52, s52, 64
	s_addc_u32 s53, s53, 0
	s_waitcnt lgkmcnt(0)
	v_mfma_f32_32x32x16_bf16 v[102:117], v[182:185], v[126:129], v[102:117]
	s_add_u32 s100, s100, 64
	s_addc_u32 s101, s101, 0
	s_waitcnt lgkmcnt(0)
	s_barrier
	ds_read_b128 v[150:153], v212 offset:46080
	ds_read_b128 v[154:157], v212 offset:46112
	ds_read_b128 v[158:161], v212 offset:46144
	ds_read_b128 v[162:165], v212 offset:46176
	ds_read_b128 v[166:169], v212 offset:46208
	s_waitcnt lgkmcnt(4)
	v_mfma_f32_32x32x16_bf16 v[118:133], v[150:153], v[6:9], 0
	ds_read_b128 v[150:153], v212 offset:46240
	ds_read_b128 v[170:173], v213 offset:23040
	v_exp_f32_e32 v134, v134
	v_exp_f32_e32 v135, v135
	s_waitcnt lgkmcnt(5)
	v_mfma_f32_32x32x16_bf16 v[118:133], v[154:157], v[10:13], v[118:133]
	ds_read_b128 v[154:157], v212 offset:46272
	ds_read_b128 v[174:177], v213 offset:25600
	v_add_f32_e32 v0, v0, v134
	v_add_f32_e32 v0, v0, v135
	s_waitcnt lgkmcnt(6)
	v_mfma_f32_32x32x16_bf16 v[118:133], v[158:161], v[14:17], v[118:133]
	ds_read_b128 v[158:161], v212 offset:46304
	ds_read_b128 v[178:181], v213 offset:28160
	v_exp_f32_e32 v136, v136
	v_exp_f32_e32 v137, v137
	s_waitcnt lgkmcnt(7)
	v_mfma_f32_32x32x16_bf16 v[118:133], v[162:165], v[18:21], v[118:133]
	ds_read_b128 v[162:165], v212 offset:46336
	ds_read_b128 v[182:185], v213 offset:30720
	v_add_f32_e32 v0, v0, v136
	v_add_f32_e32 v0, v0, v137
	s_waitcnt lgkmcnt(8)
	v_mfma_f32_32x32x16_bf16 v[118:133], v[166:169], v[22:25], v[118:133]
	ds_read_b128 v[166:169], v212 offset:46368
	v_exp_f32_e32 v138, v138
	v_exp_f32_e32 v139, v139
	v_add_f32_e32 v0, v0, v138
	s_waitcnt lgkmcnt(8)
	v_mfma_f32_32x32x16_bf16 v[118:133], v[150:153], v[26:29], v[118:133]
	ds_read_b128 v[150:153], v212 offset:46400
	v_add_f32_e32 v0, v0, v139
	v_exp_f32_e32 v140, v140
	v_exp_f32_e32 v141, v141
	s_waitcnt lgkmcnt(7)
	v_mfma_f32_32x32x16_bf16 v[118:133], v[154:157], v[30:33], v[118:133]
	ds_read_b128 v[154:157], v212 offset:46432
	s_waitcnt vmcnt(9)
	ds_write_b128 v244, v[208:211] offset:0
	global_load_dwordx4 v[208:211], v248, s[56:57]
	v_add_f32_e32 v0, v0, v140
	v_add_f32_e32 v0, v0, v141
	v_cvt_pk_bf16_f32 v134, v134, v135
	s_waitcnt lgkmcnt(7)
	v_mfma_f32_32x32x16_bf16 v[118:133], v[158:161], v[34:37], v[118:133]
	s_waitcnt vmcnt(9)
	ds_write_b128 v245, v[216:219] offset:0
	global_load_dwordx4 v[216:219], v248, s[98:99] offset:-4096
	v_cvt_pk_bf16_f32 v135, v136, v137
	v_cvt_pk_bf16_f32 v136, v138, v139
	v_cvt_pk_bf16_f32 v137, v140, v141
	s_waitcnt lgkmcnt(6)
	v_mfma_f32_32x32x16_bf16 v[118:133], v[162:165], v[38:41], v[118:133]
	s_waitcnt vmcnt(9)
	ds_write_b128 v246, v[220:223] offset:0
	global_load_dwordx4 v[220:223], v248, s[98:99]
	v_exp_f32_e32 v142, v142
	v_exp_f32_e32 v143, v143
	v_add_f32_e32 v0, v0, v142
	s_waitcnt lgkmcnt(5)
	v_mfma_f32_32x32x16_bf16 v[118:133], v[166:169], v[42:45], v[118:133]
	s_waitcnt vmcnt(9)
	ds_write_b128 v247, v[236:239] offset:0
	global_load_dwordx4 v[236:239], v235, s[52:53]
	v_add_f32_e32 v0, v0, v143
	v_exp_f32_e32 v144, v144
	v_exp_f32_e32 v145, v145
	s_waitcnt lgkmcnt(5)
	v_mfma_f32_32x32x16_bf16 v[118:133], v[150:153], v[46:49], v[118:133]
	s_waitcnt vmcnt(9)
	ds_write_b128 v247, v[240:243] offset:5120
	global_load_dwordx4 v[240:243], v235, s[100:101]
	v_add_f32_e32 v0, v0, v144
	v_add_f32_e32 v0, v0, v145
	v_exp_f32_e32 v146, v146
	s_waitcnt lgkmcnt(5)
	v_mfma_f32_32x32x16_bf16 v[118:133], v[154:157], v[50:53], v[118:133]
	v_exp_f32_e32 v147, v147
	v_add_f32_e32 v0, v0, v146
	v_add_f32_e32 v0, v0, v147
	v_mfma_f32_32x32x16_bf16 v[54:69], v[170:173], v[134:137], v[54:69]
	ds_read_b128 v[170:173], v213 offset:23072
	v_exp_f32_e32 v148, v148
	v_exp_f32_e32 v149, v149
	v_mfma_f32_32x32x16_bf16 v[70:85], v[174:177], v[134:137], v[70:85]
	ds_read_b128 v[174:177], v213 offset:25632
	v_add_f32_e32 v0, v0, v148
	v_add_f32_e32 v0, v0, v149
	v_mfma_f32_32x32x16_bf16 v[86:101], v[178:181], v[134:137], v[86:101]
	ds_read_b128 v[178:181], v213 offset:28192
	v_cvt_pk_bf16_f32 v142, v142, v143
	v_cvt_pk_bf16_f32 v143, v144, v145
	v_mfma_f32_32x32x16_bf16 v[102:117], v[182:185], v[134:137], v[102:117]
	ds_read_b128 v[182:185], v213 offset:30752
	v_cvt_pk_bf16_f32 v144, v146, v147
	v_cvt_pk_bf16_f32 v145, v148, v149
	s_waitcnt lgkmcnt(3)
	s_nop 1
	v_mfma_f32_32x32x16_bf16 v[54:69], v[170:173], v[142:145], v[54:69]
	s_add_u32 s56, s56, 0x3000
	s_addc_u32 s57, s57, 0
	s_waitcnt lgkmcnt(2)
	v_mfma_f32_32x32x16_bf16 v[70:85], v[174:177], v[142:145], v[70:85]
	s_add_u32 s98, s98, 0x3000
	s_addc_u32 s99, s99, 0
	s_waitcnt lgkmcnt(1)
	v_mfma_f32_32x32x16_bf16 v[86:101], v[178:181], v[142:145], v[86:101]
	s_add_u32 s52, s52, 64
	s_addc_u32 s53, s53, 0
	s_waitcnt lgkmcnt(0)
	v_mfma_f32_32x32x16_bf16 v[102:117], v[182:185], v[142:145], v[102:117]
	s_add_u32 s100, s100, 64
	s_addc_u32 s101, s101, 0
	s_waitcnt lgkmcnt(0)
	s_barrier
; __device__ __forceinline__ void attn_item(const Params& p, int b, int h, int qt, float shift, unsigned char* smem) {
;     ...
;   ATT_STEP(sB, sA, ntile - 1);
;   {
;     bf16x8 vfr[4];
;     ATT_VLOAD((ntile - 1) % 3, 0);
;     ATT_SHIFT(sB);
;     ATT_FINISH(sB, (ntile - 1) % 3);
	ds_read_b128 v[150:153], v212 offset:0
	ds_read_b128 v[154:157], v212 offset:32
	ds_read_b128 v[158:161], v212 offset:64
	ds_read_b128 v[162:165], v212 offset:96
	ds_read_b128 v[166:169], v212 offset:128
	s_waitcnt lgkmcnt(4)
	v_mfma_f32_32x32x16_bf16 v[134:149], v[150:153], v[6:9], 0
	ds_read_b128 v[150:153], v212 offset:160
	ds_read_b128 v[170:173], v213 offset:46080
	v_exp_f32_e32 v118, v118
	v_exp_f32_e32 v119, v119
	s_waitcnt lgkmcnt(5)
	v_mfma_f32_32x32x16_bf16 v[134:149], v[154:157], v[10:13], v[134:149]
	ds_read_b128 v[154:157], v212 offset:192
	ds_read_b128 v[174:177], v213 offset:48640
	v_add_f32_e32 v0, v0, v118
	v_add_f32_e32 v0, v0, v119
	s_waitcnt lgkmcnt(6)
	v_mfma_f32_32x32x16_bf16 v[134:149], v[158:161], v[14:17], v[134:149]
	ds_read_b128 v[158:161], v212 offset:224
	ds_read_b128 v[178:181], v213 offset:51200
	v_exp_f32_e32 v120, v120
	v_exp_f32_e32 v121, v121
	s_waitcnt lgkmcnt(7)
	v_mfma_f32_32x32x16_bf16 v[134:149], v[162:165], v[18:21], v[134:149]
	ds_read_b128 v[162:165], v212 offset:256
	ds_read_b128 v[182:185], v213 offset:53760
	v_add_f32_e32 v0, v0, v120
	v_add_f32_e32 v0, v0, v121
	s_waitcnt lgkmcnt(8)
	v_mfma_f32_32x32x16_bf16 v[134:149], v[166:169], v[22:25], v[134:149]
	ds_read_b128 v[166:169], v212 offset:288
	v_exp_f32_e32 v122, v122
	v_exp_f32_e32 v123, v123
	v_add_f32_e32 v0, v0, v122
	s_waitcnt lgkmcnt(8)
	v_mfma_f32_32x32x16_bf16 v[134:149], v[150:153], v[26:29], v[134:149]
	ds_read_b128 v[150:153], v212 offset:320
	v_add_f32_e32 v0, v0, v123
	v_exp_f32_e32 v124, v124
	v_exp_f32_e32 v125, v125
	s_waitcnt lgkmcnt(7)
	v_mfma_f32_32x32x16_bf16 v[134:149], v[154:157], v[30:33], v[134:149]
	ds_read_b128 v[154:157], v212 offset:352
	s_waitcnt vmcnt(9)
	ds_write_b128 v244, v[188:191] offset:23040
	v_add_f32_e32 v0, v0, v124
	v_add_f32_e32 v0, v0, v125
	v_cvt_pk_bf16_f32 v118, v118, v119
	s_waitcnt lgkmcnt(7)
	v_mfma_f32_32x32x16_bf16 v[134:149], v[158:161], v[34:37], v[134:149]
	s_waitcnt vmcnt(8)
	ds_write_b128 v245, v[192:195] offset:23040
	v_cvt_pk_bf16_f32 v119, v120, v121
	v_cvt_pk_bf16_f32 v120, v122, v123
	v_cvt_pk_bf16_f32 v121, v124, v125
	s_waitcnt lgkmcnt(6)
	v_mfma_f32_32x32x16_bf16 v[134:149], v[162:165], v[38:41], v[134:149]
	s_waitcnt vmcnt(7)
	ds_write_b128 v246, v[196:199] offset:23040
	v_exp_f32_e32 v126, v126
	v_exp_f32_e32 v127, v127
	v_add_f32_e32 v0, v0, v126
	s_waitcnt lgkmcnt(5)
	v_mfma_f32_32x32x16_bf16 v[134:149], v[166:169], v[42:45], v[134:149]
	s_waitcnt vmcnt(6)
	ds_write_b128 v247, v[200:203] offset:23040
	v_add_f32_e32 v0, v0, v127
	v_exp_f32_e32 v128, v128
	v_exp_f32_e32 v129, v129
	s_waitcnt lgkmcnt(5)
	v_mfma_f32_32x32x16_bf16 v[134:149], v[150:153], v[46:49], v[134:149]
	s_waitcnt vmcnt(5)
	ds_write_b128 v247, v[204:207] offset:28160
	v_add_f32_e32 v0, v0, v128
	v_add_f32_e32 v0, v0, v129
	v_exp_f32_e32 v130, v130
	s_waitcnt lgkmcnt(5)
	v_mfma_f32_32x32x16_bf16 v[134:149], v[154:157], v[50:53], v[134:149]
	v_exp_f32_e32 v131, v131
	v_add_f32_e32 v0, v0, v130
	v_add_f32_e32 v0, v0, v131
	v_mfma_f32_32x32x16_bf16 v[54:69], v[170:173], v[118:121], v[54:69]
	ds_read_b128 v[170:173], v213 offset:46112
	v_exp_f32_e32 v132, v132
	v_exp_f32_e32 v133, v133
	v_mfma_f32_32x32x16_bf16 v[70:85], v[174:177], v[118:121], v[70:85]
	ds_read_b128 v[174:177], v213 offset:48672
	v_add_f32_e32 v0, v0, v132
	v_add_f32_e32 v0, v0, v133
	v_mfma_f32_32x32x16_bf16 v[86:101], v[178:181], v[118:121], v[86:101]
	ds_read_b128 v[178:181], v213 offset:51232
	v_cvt_pk_bf16_f32 v126, v126, v127
	v_cvt_pk_bf16_f32 v127, v128, v129
	v_mfma_f32_32x32x16_bf16 v[102:117], v[182:185], v[118:121], v[102:117]
	ds_read_b128 v[182:185], v213 offset:53792
	v_cvt_pk_bf16_f32 v128, v130, v131
	v_cvt_pk_bf16_f32 v129, v132, v133
	s_waitcnt lgkmcnt(3)
	s_nop 1
	v_mfma_f32_32x32x16_bf16 v[54:69], v[170:173], v[126:129], v[54:69]
	s_waitcnt lgkmcnt(2)
	v_mfma_f32_32x32x16_bf16 v[70:85], v[174:177], v[126:129], v[70:85]
	s_waitcnt lgkmcnt(1)
	v_mfma_f32_32x32x16_bf16 v[86:101], v[178:181], v[126:129], v[86:101]
	s_waitcnt lgkmcnt(0)
	v_mfma_f32_32x32x16_bf16 v[102:117], v[182:185], v[126:129], v[102:117]
	s_waitcnt lgkmcnt(0)
	s_barrier
	ds_read_b128 v[150:153], v212 offset:23040
	ds_read_b128 v[154:157], v212 offset:23072
	ds_read_b128 v[158:161], v212 offset:23104
	ds_read_b128 v[162:165], v212 offset:23136
	ds_read_b128 v[166:169], v212 offset:23168
	s_waitcnt lgkmcnt(4)
	v_mfma_f32_32x32x16_bf16 v[118:133], v[150:153], v[6:9], 0
	ds_read_b128 v[150:153], v212 offset:23200
	ds_read_b128 v[170:173], v213 offset:0
	v_exp_f32_e32 v134, v134
	v_exp_f32_e32 v135, v135
	s_waitcnt lgkmcnt(5)
	v_mfma_f32_32x32x16_bf16 v[118:133], v[154:157], v[10:13], v[118:133]
	ds_read_b128 v[154:157], v212 offset:23232
	ds_read_b128 v[174:177], v213 offset:2560
	v_add_f32_e32 v0, v0, v134
	v_add_f32_e32 v0, v0, v135
	s_waitcnt lgkmcnt(6)
	v_mfma_f32_32x32x16_bf16 v[118:133], v[158:161], v[14:17], v[118:133]
	ds_read_b128 v[158:161], v212 offset:23264
	ds_read_b128 v[178:181], v213 offset:5120
	v_exp_f32_e32 v136, v136
	v_exp_f32_e32 v137, v137
	s_waitcnt lgkmcnt(7)
	v_mfma_f32_32x32x16_bf16 v[118:133], v[162:165], v[18:21], v[118:133]
	ds_read_b128 v[162:165], v212 offset:23296
	ds_read_b128 v[182:185], v213 offset:7680
	v_add_f32_e32 v0, v0, v136
	v_add_f32_e32 v0, v0, v137
	s_waitcnt lgkmcnt(8)
	v_mfma_f32_32x32x16_bf16 v[118:133], v[166:169], v[22:25], v[118:133]
	ds_read_b128 v[166:169], v212 offset:23328
	v_exp_f32_e32 v138, v138
	v_exp_f32_e32 v139, v139
	v_add_f32_e32 v0, v0, v138
	s_waitcnt lgkmcnt(8)
	v_mfma_f32_32x32x16_bf16 v[118:133], v[150:153], v[26:29], v[118:133]
	ds_read_b128 v[150:153], v212 offset:23360
	v_add_f32_e32 v0, v0, v139
	v_exp_f32_e32 v140, v140
	v_exp_f32_e32 v141, v141
	s_waitcnt lgkmcnt(7)
	v_mfma_f32_32x32x16_bf16 v[118:133], v[154:157], v[30:33], v[118:133]
	ds_read_b128 v[154:157], v212 offset:23392
	s_waitcnt vmcnt(4)
	ds_write_b128 v244, v[208:211] offset:46080
	v_add_f32_e32 v0, v0, v140
	v_add_f32_e32 v0, v0, v141
	v_cvt_pk_bf16_f32 v134, v134, v135
	s_waitcnt lgkmcnt(7)
	v_mfma_f32_32x32x16_bf16 v[118:133], v[158:161], v[34:37], v[118:133]
	s_waitcnt vmcnt(3)
	ds_write_b128 v245, v[216:219] offset:46080
	v_cvt_pk_bf16_f32 v135, v136, v137
	v_cvt_pk_bf16_f32 v136, v138, v139
	v_cvt_pk_bf16_f32 v137, v140, v141
	s_waitcnt lgkmcnt(6)
	v_mfma_f32_32x32x16_bf16 v[118:133], v[162:165], v[38:41], v[118:133]
	s_waitcnt vmcnt(2)
	ds_write_b128 v246, v[220:223] offset:46080
	v_exp_f32_e32 v142, v142
	v_exp_f32_e32 v143, v143
	v_add_f32_e32 v0, v0, v142
	s_waitcnt lgkmcnt(5)
	v_mfma_f32_32x32x16_bf16 v[118:133], v[166:169], v[42:45], v[118:133]
	s_waitcnt vmcnt(1)
	ds_write_b128 v247, v[236:239] offset:46080
	v_add_f32_e32 v0, v0, v143
	v_exp_f32_e32 v144, v144
	v_exp_f32_e32 v145, v145
	s_waitcnt lgkmcnt(5)
	v_mfma_f32_32x32x16_bf16 v[118:133], v[150:153], v[46:49], v[118:133]
	s_waitcnt vmcnt(0)
	ds_write_b128 v247, v[240:243] offset:51200
	v_add_f32_e32 v0, v0, v144
	v_add_f32_e32 v0, v0, v145
	v_exp_f32_e32 v146, v146
	s_waitcnt lgkmcnt(5)
	v_mfma_f32_32x32x16_bf16 v[118:133], v[154:157], v[50:53], v[118:133]
	v_exp_f32_e32 v147, v147
	v_add_f32_e32 v0, v0, v146
	v_add_f32_e32 v0, v0, v147
	v_mfma_f32_32x32x16_bf16 v[54:69], v[170:173], v[134:137], v[54:69]
	ds_read_b128 v[170:173], v213 offset:32
	v_exp_f32_e32 v148, v148
	v_exp_f32_e32 v149, v149
	v_mfma_f32_32x32x16_bf16 v[70:85], v[174:177], v[134:137], v[70:85]
	ds_read_b128 v[174:177], v213 offset:2592
	v_add_f32_e32 v0, v0, v148
	v_add_f32_e32 v0, v0, v149
	v_mfma_f32_32x32x16_bf16 v[86:101], v[178:181], v[134:137], v[86:101]
	ds_read_b128 v[178:181], v213 offset:5152
	v_cvt_pk_bf16_f32 v142, v142, v143
	v_cvt_pk_bf16_f32 v143, v144, v145
	v_mfma_f32_32x32x16_bf16 v[102:117], v[182:185], v[134:137], v[102:117]
	ds_read_b128 v[182:185], v213 offset:7712
	v_cvt_pk_bf16_f32 v144, v146, v147
	v_cvt_pk_bf16_f32 v145, v148, v149
	s_waitcnt lgkmcnt(3)
	s_nop 1
	v_mfma_f32_32x32x16_bf16 v[54:69], v[170:173], v[142:145], v[54:69]
	s_waitcnt lgkmcnt(2)
	v_mfma_f32_32x32x16_bf16 v[70:85], v[174:177], v[142:145], v[70:85]
	s_waitcnt lgkmcnt(1)
	v_mfma_f32_32x32x16_bf16 v[86:101], v[178:181], v[142:145], v[86:101]
	s_waitcnt lgkmcnt(0)
	v_mfma_f32_32x32x16_bf16 v[102:117], v[182:185], v[142:145], v[102:117]
	s_waitcnt lgkmcnt(0)
	s_barrier
	ds_read_b128 v[150:153], v212 offset:46080
	ds_read_b128 v[154:157], v212 offset:46112
	ds_read_b128 v[158:161], v212 offset:46144
	ds_read_b128 v[162:165], v212 offset:46176
	ds_read_b128 v[166:169], v212 offset:46208
	s_waitcnt lgkmcnt(4)
	v_mfma_f32_32x32x16_bf16 v[134:149], v[150:153], v[6:9], 0
	ds_read_b128 v[150:153], v212 offset:46240
	ds_read_b128 v[170:173], v213 offset:23040
	v_exp_f32_e32 v118, v118
	v_exp_f32_e32 v119, v119
	s_waitcnt lgkmcnt(5)
	v_mfma_f32_32x32x16_bf16 v[134:149], v[154:157], v[10:13], v[134:149]
	ds_read_b128 v[154:157], v212 offset:46272
	ds_read_b128 v[174:177], v213 offset:25600
	v_add_f32_e32 v0, v0, v118
	v_add_f32_e32 v0, v0, v119
	s_waitcnt lgkmcnt(6)
	v_mfma_f32_32x32x16_bf16 v[134:149], v[158:161], v[14:17], v[134:149]
	ds_read_b128 v[158:161], v212 offset:46304
	ds_read_b128 v[178:181], v213 offset:28160
	v_exp_f32_e32 v120, v120
	v_exp_f32_e32 v121, v121
	s_waitcnt lgkmcnt(7)
	v_mfma_f32_32x32x16_bf16 v[134:149], v[162:165], v[18:21], v[134:149]
	ds_read_b128 v[162:165], v212 offset:46336
	ds_read_b128 v[182:185], v213 offset:30720
	v_add_f32_e32 v0, v0, v120
	v_add_f32_e32 v0, v0, v121
	s_waitcnt lgkmcnt(8)
	v_mfma_f32_32x32x16_bf16 v[134:149], v[166:169], v[22:25], v[134:149]
	ds_read_b128 v[166:169], v212 offset:46368
	v_exp_f32_e32 v122, v122
	v_exp_f32_e32 v123, v123
	v_add_f32_e32 v0, v0, v122
	s_waitcnt lgkmcnt(8)
	v_mfma_f32_32x32x16_bf16 v[134:149], v[150:153], v[26:29], v[134:149]
	ds_read_b128 v[150:153], v212 offset:46400
	v_add_f32_e32 v0, v0, v123
	v_exp_f32_e32 v124, v124
	v_exp_f32_e32 v125, v125
	s_waitcnt lgkmcnt(7)
	v_mfma_f32_32x32x16_bf16 v[134:149], v[154:157], v[30:33], v[134:149]
	ds_read_b128 v[154:157], v212 offset:46432
	v_add_f32_e32 v0, v0, v124
	v_add_f32_e32 v0, v0, v125
	v_cvt_pk_bf16_f32 v118, v118, v119
	s_waitcnt lgkmcnt(6)
	v_mfma_f32_32x32x16_bf16 v[134:149], v[158:161], v[34:37], v[134:149]
	v_cvt_pk_bf16_f32 v119, v120, v121
	v_cvt_pk_bf16_f32 v120, v122, v123
	v_cvt_pk_bf16_f32 v121, v124, v125
	s_waitcnt lgkmcnt(4)
	v_mfma_f32_32x32x16_bf16 v[134:149], v[162:165], v[38:41], v[134:149]
	v_exp_f32_e32 v126, v126
	v_exp_f32_e32 v127, v127
	v_add_f32_e32 v0, v0, v126
	s_waitcnt lgkmcnt(2)
	v_mfma_f32_32x32x16_bf16 v[134:149], v[166:169], v[42:45], v[134:149]
	v_add_f32_e32 v0, v0, v127
	v_exp_f32_e32 v128, v128
	v_exp_f32_e32 v129, v129
	s_waitcnt lgkmcnt(1)
	v_mfma_f32_32x32x16_bf16 v[134:149], v[150:153], v[46:49], v[134:149]
	v_add_f32_e32 v0, v0, v128
	v_add_f32_e32 v0, v0, v129
	v_exp_f32_e32 v130, v130
	s_waitcnt lgkmcnt(0)
	v_mfma_f32_32x32x16_bf16 v[134:149], v[154:157], v[50:53], v[134:149]
	v_exp_f32_e32 v131, v131
	v_add_f32_e32 v0, v0, v130
	v_add_f32_e32 v0, v0, v131
	v_mfma_f32_32x32x16_bf16 v[54:69], v[170:173], v[118:121], v[54:69]
	ds_read_b128 v[170:173], v213 offset:23072
	v_exp_f32_e32 v132, v132
	v_exp_f32_e32 v133, v133
	v_mfma_f32_32x32x16_bf16 v[70:85], v[174:177], v[118:121], v[70:85]
	ds_read_b128 v[174:177], v213 offset:25632
	v_add_f32_e32 v0, v0, v132
	v_add_f32_e32 v0, v0, v133
	v_mfma_f32_32x32x16_bf16 v[86:101], v[178:181], v[118:121], v[86:101]
	ds_read_b128 v[178:181], v213 offset:28192
	v_cvt_pk_bf16_f32 v126, v126, v127
	v_cvt_pk_bf16_f32 v127, v128, v129
	v_mfma_f32_32x32x16_bf16 v[102:117], v[182:185], v[118:121], v[102:117]
	ds_read_b128 v[182:185], v213 offset:30752
	v_cvt_pk_bf16_f32 v128, v130, v131
	v_cvt_pk_bf16_f32 v129, v132, v133
	s_waitcnt lgkmcnt(3)
	s_nop 1
	v_mfma_f32_32x32x16_bf16 v[54:69], v[170:173], v[126:129], v[54:69]
	s_waitcnt lgkmcnt(2)
	v_mfma_f32_32x32x16_bf16 v[70:85], v[174:177], v[126:129], v[70:85]
	s_waitcnt lgkmcnt(1)
	v_mfma_f32_32x32x16_bf16 v[86:101], v[178:181], v[126:129], v[86:101]
	s_waitcnt lgkmcnt(0)
	v_mfma_f32_32x32x16_bf16 v[102:117], v[182:185], v[126:129], v[102:117]
	s_waitcnt lgkmcnt(0)
	s_barrier
; __device__ __forceinline__ void attn_item(const Params& p, int b, int h, int qt, float shift, unsigned char* smem) {
;     ...
;   {
;     bf16x8 vfr[4];
;     ATT_VLOAD((ntile - 1) % 3, 0);
;     ATT_SHIFT(sB);
;     ATT_FINISH(sB, (ntile - 1) % 3);
;   }
;   __syncthreads();
;     ...
; #pragma unroll
;   for (int qi = 0; qi < 2; ++qi) {
;     float ls = qi ? lrun1 : lrun0;
;     ls += __shfl_xor(ls, 16);
;     ls += __shfl_xor(ls, 32);
;     const float inv = 1.f / ls;
;     const int pos = qt * 128 + wid * 32 + qi * 16 + l16;
;     const int row = (pos < CTX) ? (T_LAT + b * CTX + pos) : (b * SEQ + pos - CTX);
;     u16* orow = p.YM + (size_t)row * 1024 + 512 + h * 128 + quad * 4;
; #pragma unroll
;     for (int vt = 0; vt < 8; ++vt) {
;       u32x2 pk;
;       pk.x = pack2(o[vt][qi][0] * inv, o[vt][qi][1] * inv);
;       pk.y = pack2(o[vt][qi][2] * inv, o[vt][qi][3] * inv);
;       *(u32x2*)(orow + vt * 16) = pk;
;     }
;   }
	ds_read_b128 v[170:173], v213 offset:46080
	ds_read_b128 v[174:177], v213 offset:48640
	ds_read_b128 v[178:181], v213 offset:51200
	ds_read_b128 v[182:185], v213 offset:53760
	v_exp_f32_e32 v134, v134
	v_exp_f32_e32 v135, v135
	v_add_f32_e32 v0, v0, v134
	v_add_f32_e32 v0, v0, v135
	v_exp_f32_e32 v136, v136
	v_exp_f32_e32 v137, v137
	v_add_f32_e32 v0, v0, v136
	v_add_f32_e32 v0, v0, v137
	v_exp_f32_e32 v138, v138
	v_exp_f32_e32 v139, v139
	v_add_f32_e32 v0, v0, v138
	v_add_f32_e32 v0, v0, v139
	v_exp_f32_e32 v140, v140
	v_exp_f32_e32 v141, v141
	v_add_f32_e32 v0, v0, v140
	v_add_f32_e32 v0, v0, v141
	v_cvt_pk_bf16_f32 v134, v134, v135
	v_cvt_pk_bf16_f32 v135, v136, v137
	v_cvt_pk_bf16_f32 v136, v138, v139
	v_cvt_pk_bf16_f32 v137, v140, v141
	v_exp_f32_e32 v142, v142
	v_exp_f32_e32 v143, v143
	v_add_f32_e32 v0, v0, v142
	v_add_f32_e32 v0, v0, v143
	v_exp_f32_e32 v144, v144
	v_exp_f32_e32 v145, v145
	v_add_f32_e32 v0, v0, v144
	v_add_f32_e32 v0, v0, v145
	v_exp_f32_e32 v146, v146
	v_exp_f32_e32 v147, v147
	v_add_f32_e32 v0, v0, v146
	v_add_f32_e32 v0, v0, v147
	v_exp_f32_e32 v148, v148
	v_exp_f32_e32 v149, v149
	v_add_f32_e32 v0, v0, v148
	v_add_f32_e32 v0, v0, v149
	v_cvt_pk_bf16_f32 v142, v142, v143
	v_cvt_pk_bf16_f32 v143, v144, v145
	v_cvt_pk_bf16_f32 v144, v146, v147
	v_cvt_pk_bf16_f32 v145, v148, v149
	s_nop 1
	s_waitcnt lgkmcnt(3)
	v_mfma_f32_32x32x16_bf16 v[54:69], v[170:173], v[134:137], v[54:69]
	ds_read_b128 v[170:173], v213 offset:46112
	s_waitcnt lgkmcnt(3)
	v_mfma_f32_32x32x16_bf16 v[70:85], v[174:177], v[134:137], v[70:85]
	ds_read_b128 v[174:177], v213 offset:48672
	s_waitcnt lgkmcnt(3)
	v_mfma_f32_32x32x16_bf16 v[86:101], v[178:181], v[134:137], v[86:101]
	ds_read_b128 v[178:181], v213 offset:51232
	s_waitcnt lgkmcnt(3)
	v_mfma_f32_32x32x16_bf16 v[102:117], v[182:185], v[134:137], v[102:117]
	ds_read_b128 v[182:185], v213 offset:53792
	s_waitcnt lgkmcnt(3)
	v_mfma_f32_32x32x16_bf16 v[54:69], v[170:173], v[142:145], v[54:69]
	s_waitcnt lgkmcnt(2)
	v_mfma_f32_32x32x16_bf16 v[70:85], v[174:177], v[142:145], v[70:85]
	s_waitcnt lgkmcnt(1)
	v_mfma_f32_32x32x16_bf16 v[86:101], v[178:181], v[142:145], v[86:101]
	s_waitcnt lgkmcnt(0)
	v_mfma_f32_32x32x16_bf16 v[102:117], v[182:185], v[142:145], v[102:117]
	ds_bpermute_b32 v118, v229, v0
	v_and_b32_e32 v119, 31, v187
	v_bfe_u32 v120, v187, 5, 1
	v_lshlrev_b32_e32 v119, 11, v119
	v_lshl_add_u32 v123, v120, 3, v119
	s_waitcnt lgkmcnt(0)
	v_add_f32_e32 v0, v0, v118
	v_div_scale_f32 v118, s[0:1], v0, v0, 1.0
	v_rcp_f32_e32 v119, v118
	s_nop 0
	v_fma_f32 v120, -v118, v119, 1.0
	v_fmac_f32_e32 v119, v120, v119
	v_div_scale_f32 v120, vcc, 1.0, v0, 1.0
	v_mul_f32_e32 v121, v120, v119
	v_fma_f32 v122, -v118, v121, v120
	v_fmac_f32_e32 v121, v122, v119
	v_fma_f32 v118, -v118, v121, v120
	v_div_fmas_f32 v118, v118, v119, v121
	v_div_fixup_f32 v0, v118, v0, 1.0
	s_nop 4
	v_mul_f32_e32 v54, v54, v0
	v_mul_f32_e32 v55, v55, v0
	v_mul_f32_e32 v56, v56, v0
	v_mul_f32_e32 v57, v57, v0
	v_cvt_pk_bf16_f32 v54, v54, v55
	v_cvt_pk_bf16_f32 v55, v56, v57
	global_store_dwordx2 v123, v[54:55], s[88:89] offset:0
	v_mul_f32_e32 v58, v58, v0
	v_mul_f32_e32 v59, v59, v0
	v_mul_f32_e32 v60, v60, v0
	v_mul_f32_e32 v61, v61, v0
	v_cvt_pk_bf16_f32 v58, v58, v59
	v_cvt_pk_bf16_f32 v59, v60, v61
	global_store_dwordx2 v123, v[58:59], s[88:89] offset:16
	v_mul_f32_e32 v62, v62, v0
	v_mul_f32_e32 v63, v63, v0
	v_mul_f32_e32 v64, v64, v0
	v_mul_f32_e32 v65, v65, v0
	v_cvt_pk_bf16_f32 v62, v62, v63
	v_cvt_pk_bf16_f32 v63, v64, v65
	global_store_dwordx2 v123, v[62:63], s[88:89] offset:32
	v_mul_f32_e32 v66, v66, v0
	v_mul_f32_e32 v67, v67, v0
	v_mul_f32_e32 v68, v68, v0
	v_mul_f32_e32 v69, v69, v0
	v_cvt_pk_bf16_f32 v66, v66, v67
	v_cvt_pk_bf16_f32 v67, v68, v69
	global_store_dwordx2 v123, v[66:67], s[88:89] offset:48
	v_mul_f32_e32 v70, v70, v0
	v_mul_f32_e32 v71, v71, v0
	v_mul_f32_e32 v72, v72, v0
	v_mul_f32_e32 v73, v73, v0
	v_cvt_pk_bf16_f32 v70, v70, v71
	v_cvt_pk_bf16_f32 v71, v72, v73
	global_store_dwordx2 v123, v[70:71], s[88:89] offset:64
	v_mul_f32_e32 v74, v74, v0
	v_mul_f32_e32 v75, v75, v0
	v_mul_f32_e32 v76, v76, v0
	v_mul_f32_e32 v77, v77, v0
	v_cvt_pk_bf16_f32 v74, v74, v75
	v_cvt_pk_bf16_f32 v75, v76, v77
	global_store_dwordx2 v123, v[74:75], s[88:89] offset:80
	v_mul_f32_e32 v78, v78, v0
	v_mul_f32_e32 v79, v79, v0
	v_mul_f32_e32 v80, v80, v0
	v_mul_f32_e32 v81, v81, v0
	v_cvt_pk_bf16_f32 v78, v78, v79
	v_cvt_pk_bf16_f32 v79, v80, v81
	global_store_dwordx2 v123, v[78:79], s[88:89] offset:96
	v_mul_f32_e32 v82, v82, v0
	v_mul_f32_e32 v83, v83, v0
	v_mul_f32_e32 v84, v84, v0
	v_mul_f32_e32 v85, v85, v0
	v_cvt_pk_bf16_f32 v82, v82, v83
	v_cvt_pk_bf16_f32 v83, v84, v85
	global_store_dwordx2 v123, v[82:83], s[88:89] offset:112
	v_mul_f32_e32 v86, v86, v0
	v_mul_f32_e32 v87, v87, v0
	v_mul_f32_e32 v88, v88, v0
	v_mul_f32_e32 v89, v89, v0
	v_cvt_pk_bf16_f32 v86, v86, v87
	v_cvt_pk_bf16_f32 v87, v88, v89
	global_store_dwordx2 v123, v[86:87], s[88:89] offset:128
	v_mul_f32_e32 v90, v90, v0
	v_mul_f32_e32 v91, v91, v0
	v_mul_f32_e32 v92, v92, v0
	v_mul_f32_e32 v93, v93, v0
	v_cvt_pk_bf16_f32 v90, v90, v91
	v_cvt_pk_bf16_f32 v91, v92, v93
	global_store_dwordx2 v123, v[90:91], s[88:89] offset:144
	v_mul_f32_e32 v94, v94, v0
	v_mul_f32_e32 v95, v95, v0
	v_mul_f32_e32 v96, v96, v0
	v_mul_f32_e32 v97, v97, v0
	v_cvt_pk_bf16_f32 v94, v94, v95
	v_cvt_pk_bf16_f32 v95, v96, v97
	global_store_dwordx2 v123, v[94:95], s[88:89] offset:160
	v_mul_f32_e32 v98, v98, v0
	v_mul_f32_e32 v99, v99, v0
	v_mul_f32_e32 v100, v100, v0
	v_mul_f32_e32 v101, v101, v0
	v_cvt_pk_bf16_f32 v98, v98, v99
	v_cvt_pk_bf16_f32 v99, v100, v101
	global_store_dwordx2 v123, v[98:99], s[88:89] offset:176
	v_mul_f32_e32 v102, v102, v0
	v_mul_f32_e32 v103, v103, v0
	v_mul_f32_e32 v104, v104, v0
	v_mul_f32_e32 v105, v105, v0
	v_cvt_pk_bf16_f32 v102, v102, v103
	v_cvt_pk_bf16_f32 v103, v104, v105
	global_store_dwordx2 v123, v[102:103], s[88:89] offset:192
	v_mul_f32_e32 v106, v106, v0
	v_mul_f32_e32 v107, v107, v0
	v_mul_f32_e32 v108, v108, v0
	v_mul_f32_e32 v109, v109, v0
	v_cvt_pk_bf16_f32 v106, v106, v107
	v_cvt_pk_bf16_f32 v107, v108, v109
	global_store_dwordx2 v123, v[106:107], s[88:89] offset:208
	v_mul_f32_e32 v110, v110, v0
	v_mul_f32_e32 v111, v111, v0
	v_mul_f32_e32 v112, v112, v0
	v_mul_f32_e32 v113, v113, v0
	v_cvt_pk_bf16_f32 v110, v110, v111
	v_cvt_pk_bf16_f32 v111, v112, v113
	global_store_dwordx2 v123, v[110:111], s[88:89] offset:224
	v_mul_f32_e32 v114, v114, v0
	v_mul_f32_e32 v115, v115, v0
	v_mul_f32_e32 v116, v116, v0
	v_mul_f32_e32 v117, v117, v0
	v_cvt_pk_bf16_f32 v114, v114, v115
	v_cvt_pk_bf16_f32 v115, v116, v117
	global_store_dwordx2 v123, v[114:115], s[88:89] offset:240
	s_waitcnt lgkmcnt(0)
	s_barrier
	s_mov_b32 s47, s95
	s_add_i32 s50, s50, s3
	s_cmp_gt_i32 s50, 63
	s_cbranch_scc0 .LBB0_766
	s_branch .LBB0_776

